# hand-scheduled in-place SwiGLU epilogue; trailing-half restore barrier moved behind next-unit scheduling in all 4 multi-unit GEMM loops; sink load no longer waited for before the Q loads
# speedup vs baseline: 1.0068x; 1.0064x over previous
.LBB0_373:
	s_add_u32 s40, s40, 0x80
	s_addc_u32 s41, s41, 0
	s_add_u32 s34, s42, 0x100
	v_mov_b32_e32 v2, 0
	s_addc_u32 s48, s43, 0
	s_mov_b32 s42, 0
	v_mov_b32_e32 v3, v2
	v_mov_b32_e32 v4, v2
	v_mov_b32_e32 v5, v2
	v_mov_b32_e32 v6, v2
	v_mov_b32_e32 v7, v2
	v_mov_b32_e32 v8, v2
	v_mov_b32_e32 v9, v2
	v_mov_b32_e32 v18, v2
	v_mov_b32_e32 v19, v2
	v_mov_b32_e32 v20, v2
	v_mov_b32_e32 v21, v2
	v_mov_b32_e32 v22, v2
	v_mov_b32_e32 v23, v2
	v_mov_b32_e32 v24, v2
	v_mov_b32_e32 v25, v2
	v_mov_b32_e32 v34, v2
	v_mov_b32_e32 v35, v2
	v_mov_b32_e32 v36, v2
	v_mov_b32_e32 v37, v2
	v_mov_b32_e32 v38, v2
	v_mov_b32_e32 v39, v2
	v_mov_b32_e32 v40, v2
	v_mov_b32_e32 v41, v2
	v_mov_b32_e32 v50, v2
	v_mov_b32_e32 v51, v2
	v_mov_b32_e32 v52, v2
	v_mov_b32_e32 v53, v2
	v_mov_b32_e32 v54, v2
	v_mov_b32_e32 v55, v2
	v_mov_b32_e32 v56, v2
	v_mov_b32_e32 v57, v2
	v_mov_b32_e32 v10, v2
	v_mov_b32_e32 v11, v2
	v_mov_b32_e32 v12, v2
	v_mov_b32_e32 v13, v2
	v_mov_b32_e32 v14, v2
	v_mov_b32_e32 v15, v2
	v_mov_b32_e32 v16, v2
	v_mov_b32_e32 v17, v2
	v_mov_b32_e32 v26, v2
	v_mov_b32_e32 v27, v2
	v_mov_b32_e32 v28, v2
	v_mov_b32_e32 v29, v2
	v_mov_b32_e32 v30, v2
	v_mov_b32_e32 v31, v2
	v_mov_b32_e32 v32, v2
	v_mov_b32_e32 v33, v2
	v_mov_b32_e32 v42, v2
	v_mov_b32_e32 v43, v2
	v_mov_b32_e32 v44, v2
	v_mov_b32_e32 v45, v2
	v_mov_b32_e32 v46, v2
	v_mov_b32_e32 v47, v2
	v_mov_b32_e32 v48, v2
	v_mov_b32_e32 v49, v2
	v_mov_b32_e32 v58, v2
	v_mov_b32_e32 v59, v2
	v_mov_b32_e32 v60, v2
	v_mov_b32_e32 v61, v2
	v_mov_b32_e32 v62, v2
	v_mov_b32_e32 v63, v2
	v_mov_b32_e32 v64, v2
	v_mov_b32_e32 v65, v2
	v_mov_b32_e32 v66, v2
	v_mov_b32_e32 v67, v2
	v_mov_b32_e32 v68, v2
	v_mov_b32_e32 v69, v2
	v_mov_b32_e32 v70, v2
	v_mov_b32_e32 v71, v2
	v_mov_b32_e32 v72, v2
	v_mov_b32_e32 v73, v2
	v_mov_b32_e32 v82, v2
	v_mov_b32_e32 v83, v2
	v_mov_b32_e32 v84, v2
	v_mov_b32_e32 v85, v2
	v_mov_b32_e32 v86, v2
	v_mov_b32_e32 v87, v2
	v_mov_b32_e32 v88, v2
	v_mov_b32_e32 v89, v2
	v_mov_b32_e32 v98, v2
	v_mov_b32_e32 v99, v2
	v_mov_b32_e32 v100, v2
	v_mov_b32_e32 v101, v2
	v_mov_b32_e32 v102, v2
	v_mov_b32_e32 v103, v2
	v_mov_b32_e32 v104, v2
	v_mov_b32_e32 v105, v2
	v_mov_b32_e32 v114, v2
	v_mov_b32_e32 v115, v2
	v_mov_b32_e32 v116, v2
	v_mov_b32_e32 v117, v2
	v_mov_b32_e32 v118, v2
	v_mov_b32_e32 v119, v2
	v_mov_b32_e32 v120, v2
	v_mov_b32_e32 v121, v2
	v_mov_b32_e32 v74, v2
	v_mov_b32_e32 v75, v2
	v_mov_b32_e32 v76, v2
	v_mov_b32_e32 v77, v2
	v_mov_b32_e32 v78, v2
	v_mov_b32_e32 v79, v2
	v_mov_b32_e32 v80, v2
	v_mov_b32_e32 v81, v2
	v_mov_b32_e32 v90, v2
	v_mov_b32_e32 v91, v2
	v_mov_b32_e32 v92, v2
	v_mov_b32_e32 v93, v2
	v_mov_b32_e32 v94, v2
	v_mov_b32_e32 v95, v2
	v_mov_b32_e32 v96, v2
	v_mov_b32_e32 v97, v2
	v_mov_b32_e32 v106, v2
	v_mov_b32_e32 v107, v2
	v_mov_b32_e32 v108, v2
	v_mov_b32_e32 v109, v2
	v_mov_b32_e32 v110, v2
	v_mov_b32_e32 v111, v2
	v_mov_b32_e32 v112, v2
	v_mov_b32_e32 v113, v2
	v_mov_b32_e32 v126, v2
	v_mov_b32_e32 v127, v2
	v_mov_b32_e32 v128, v2
	v_mov_b32_e32 v129, v2
	v_mov_b32_e32 v130, v2
	v_mov_b32_e32 v131, v2
	v_mov_b32_e32 v132, v2
	v_mov_b32_e32 v133, v2
	s_cmp_eq_u32 s60, 1
	s_cbranch_scc1 .Ltb_res_skip
	s_cmp_eq_u32 s6, 0
	s_cbranch_scc1 .Ltb_res_skip
	s_barrier
.Ltb_res_skip:
.LBB0_374:
	s_add_i32 s49, s42, 2
	s_add_u32 s74, s40, 0x80
	s_addc_u32 s43, s41, 0
	s_add_i32 s76, 0, 0x10000
	s_cmp_eq_u32 s67, s42
	s_cselect_b32 s43, s3, s43
	s_cselect_b32 s42, s2, s74
	s_cselect_b32 s75, s47, s48
	s_cselect_b32 s74, s46, s34
	s_add_i32 s77, 0, 0x14000
	v_add_u32_e32 v142, s76, v196
	v_add_u32_e32 v166, s77, v196
	ds_read_b128 v[122:125], v142
	ds_read_b128 v[134:137], v142 offset:1024
	ds_read_b128 v[138:141], v142 offset:2048
	ds_read_b128 v[142:145], v142 offset:3072
	ds_read_b128 v[150:153], v166
	ds_read_b128 v[154:157], v166 offset:1024
	ds_read_b128 v[158:161], v166 offset:2048
	ds_read_b128 v[178:181], v166 offset:3072
	v_lshl_add_u64 v[166:167], s[40:41], 0, v[174:175]
	s_add_i32 m0, s54, 0xc000
	ds_read_b128 v[182:185], v200
	ds_read_b128 v[186:189], v200 offset:1024
	ds_read_b128 v[190:193], v200 offset:2048
	ds_read_b128 v[202:205], v200 offset:3072
	ds_read_b128 v[214:217], v200 offset:4096
	ds_read_b128 v[218:221], v200 offset:5120
	ds_read_b128 v[222:225], v200 offset:6144
	ds_read_b128 v[226:229], v200 offset:7168
	global_load_lds_dwordx4 v[166:167], off
	v_lshl_add_u64 v[166:167], s[40:41], 0, v[176:177]
	s_add_i32 m0, s54, 0xe000
	s_nop 0
	global_load_lds_dwordx4 v[166:167], off
	s_waitcnt vmcnt(8)
	s_waitcnt lgkmcnt(0)
	s_barrier
	s_setprio 1
	s_waitcnt lgkmcnt(0)
	v_mfma_f32_16x16x32_bf16 v[130:133], v[122:125], v[182:185], v[130:133]
	v_mfma_f32_16x16x32_bf16 v[126:129], v[138:141], v[182:185], v[126:129]
	v_mfma_f32_16x16x32_bf16 v[110:113], v[122:125], v[190:193], v[110:113]
	v_mfma_f32_16x16x32_bf16 v[106:109], v[138:141], v[190:193], v[106:109]
	v_mfma_f32_16x16x32_bf16 v[94:97], v[122:125], v[214:217], v[94:97]
	v_mfma_f32_16x16x32_bf16 v[90:93], v[138:141], v[214:217], v[90:93]
	v_mfma_f32_16x16x32_bf16 v[78:81], v[122:125], v[222:225], v[78:81]
	v_mfma_f32_16x16x32_bf16 v[74:77], v[138:141], v[222:225], v[74:77]
	v_mfma_f32_16x16x32_bf16 v[130:133], v[134:137], v[186:189], v[130:133]
	v_mfma_f32_16x16x32_bf16 v[126:129], v[142:145], v[186:189], v[126:129]
	v_mfma_f32_16x16x32_bf16 v[110:113], v[134:137], v[202:205], v[110:113]
	v_mfma_f32_16x16x32_bf16 v[106:109], v[142:145], v[202:205], v[106:109]
	v_mfma_f32_16x16x32_bf16 v[94:97], v[134:137], v[218:221], v[94:97]
	v_mfma_f32_16x16x32_bf16 v[90:93], v[142:145], v[218:221], v[90:93]
	v_mfma_f32_16x16x32_bf16 v[78:81], v[134:137], v[226:229], v[78:81]
	v_mfma_f32_16x16x32_bf16 v[74:77], v[142:145], v[226:229], v[74:77]
	s_setprio 0
	s_setprio 1
	v_mfma_f32_16x16x32_bf16 v[118:121], v[150:153], v[182:185], v[118:121]
	v_mfma_f32_16x16x32_bf16 v[114:117], v[158:161], v[182:185], v[114:117]
	v_mfma_f32_16x16x32_bf16 v[102:105], v[150:153], v[190:193], v[102:105]
	v_mfma_f32_16x16x32_bf16 v[98:101], v[158:161], v[190:193], v[98:101]
	v_mfma_f32_16x16x32_bf16 v[86:89], v[150:153], v[214:217], v[86:89]
	v_mfma_f32_16x16x32_bf16 v[82:85], v[158:161], v[214:217], v[82:85]
	v_mfma_f32_16x16x32_bf16 v[70:73], v[150:153], v[222:225], v[70:73]
	v_mfma_f32_16x16x32_bf16 v[66:69], v[158:161], v[222:225], v[66:69]
	v_mfma_f32_16x16x32_bf16 v[118:121], v[154:157], v[186:189], v[118:121]
	v_mfma_f32_16x16x32_bf16 v[114:117], v[178:181], v[186:189], v[114:117]
	v_mfma_f32_16x16x32_bf16 v[102:105], v[154:157], v[202:205], v[102:105]
	v_mfma_f32_16x16x32_bf16 v[98:101], v[178:181], v[202:205], v[98:101]
	v_mfma_f32_16x16x32_bf16 v[86:89], v[154:157], v[218:221], v[86:89]
	v_mfma_f32_16x16x32_bf16 v[82:85], v[178:181], v[218:221], v[82:85]
	v_mfma_f32_16x16x32_bf16 v[70:73], v[154:157], v[226:229], v[70:73]
	v_mfma_f32_16x16x32_bf16 v[66:69], v[178:181], v[226:229], v[66:69]
	s_setprio 0
	s_barrier
	s_add_i32 s76, s76, s51
	v_lshl_add_u64 v[166:167], s[74:75], 0, v[0:1]
	s_mov_b32 m0, s76
	ds_read_b128 v[182:185], v200 offset:16384
	ds_read_b128 v[186:189], v200 offset:17408
	ds_read_b128 v[190:193], v200 offset:18432
	ds_read_b128 v[202:205], v200 offset:19456
	ds_read_b128 v[214:217], v200 offset:20480
	ds_read_b128 v[218:221], v200 offset:21504
	ds_read_b128 v[222:225], v200 offset:22528
	ds_read_b128 v[226:229], v200 offset:23552
	global_load_lds_dwordx4 v[166:167], off
	s_add_i32 m0, s76, 0x2000
	v_lshl_add_u64 v[194:195], s[74:75], 0, v[172:173]
	s_add_u32 s74, s74, s16
	s_addc_u32 s75, s75, 0
	s_add_i32 s76, s77, s51
	global_load_lds_dwordx4 v[194:195], off
	v_lshl_add_u64 v[230:231], s[74:75], 0, v[0:1]
	s_mov_b32 m0, s76
	v_lshl_add_u64 v[232:233], s[74:75], 0, v[172:173]
	global_load_lds_dwordx4 v[230:231], off
	s_add_i32 m0, s76, 0x2000
	v_lshl_add_u64 v[234:235], s[42:43], 0, v[162:163]
	global_load_lds_dwordx4 v[232:233], off
	s_mov_b32 m0, s54
	v_lshl_add_u64 v[236:237], s[42:43], 0, v[164:165]
	global_load_lds_dwordx4 v[234:235], off
	s_mov_b32 m0, s55
	s_nop 0
	global_load_lds_dwordx4 v[236:237], off
	s_waitcnt vmcnt(8)
	s_waitcnt lgkmcnt(0)
	s_barrier
	s_setprio 1
	s_waitcnt lgkmcnt(0)
	v_mfma_f32_16x16x32_bf16 v[62:65], v[122:125], v[182:185], v[62:65]
	v_mfma_f32_16x16x32_bf16 v[58:61], v[138:141], v[182:185], v[58:61]
	v_mfma_f32_16x16x32_bf16 v[46:49], v[122:125], v[190:193], v[46:49]
	v_mfma_f32_16x16x32_bf16 v[42:45], v[138:141], v[190:193], v[42:45]
	v_mfma_f32_16x16x32_bf16 v[30:33], v[122:125], v[214:217], v[30:33]
	v_mfma_f32_16x16x32_bf16 v[26:29], v[138:141], v[214:217], v[26:29]
	v_mfma_f32_16x16x32_bf16 v[14:17], v[122:125], v[222:225], v[14:17]
	v_mfma_f32_16x16x32_bf16 v[10:13], v[138:141], v[222:225], v[10:13]
	v_mfma_f32_16x16x32_bf16 v[62:65], v[134:137], v[186:189], v[62:65]
	v_mfma_f32_16x16x32_bf16 v[58:61], v[142:145], v[186:189], v[58:61]
	v_mfma_f32_16x16x32_bf16 v[46:49], v[134:137], v[202:205], v[46:49]
	v_mfma_f32_16x16x32_bf16 v[42:45], v[142:145], v[202:205], v[42:45]
	v_mfma_f32_16x16x32_bf16 v[30:33], v[134:137], v[218:221], v[30:33]
	v_mfma_f32_16x16x32_bf16 v[26:29], v[142:145], v[218:221], v[26:29]
	v_mfma_f32_16x16x32_bf16 v[14:17], v[134:137], v[226:229], v[14:17]
	v_mfma_f32_16x16x32_bf16 v[10:13], v[142:145], v[226:229], v[10:13]
	s_setprio 0
	s_setprio 1
	v_mfma_f32_16x16x32_bf16 v[54:57], v[150:153], v[182:185], v[54:57]
	v_mfma_f32_16x16x32_bf16 v[50:53], v[158:161], v[182:185], v[50:53]
	v_mfma_f32_16x16x32_bf16 v[38:41], v[150:153], v[190:193], v[38:41]
	v_mfma_f32_16x16x32_bf16 v[34:37], v[158:161], v[190:193], v[34:37]
	v_mfma_f32_16x16x32_bf16 v[22:25], v[150:153], v[214:217], v[22:25]
	v_mfma_f32_16x16x32_bf16 v[18:21], v[158:161], v[214:217], v[18:21]
	v_mfma_f32_16x16x32_bf16 v[6:9], v[150:153], v[222:225], v[6:9]
	v_mfma_f32_16x16x32_bf16 v[2:5], v[158:161], v[222:225], v[2:5]
	v_mfma_f32_16x16x32_bf16 v[54:57], v[154:157], v[186:189], v[54:57]
	v_mfma_f32_16x16x32_bf16 v[50:53], v[178:181], v[186:189], v[50:53]
	v_mfma_f32_16x16x32_bf16 v[38:41], v[154:157], v[202:205], v[38:41]
	v_mfma_f32_16x16x32_bf16 v[34:37], v[178:181], v[202:205], v[34:37]
	v_mfma_f32_16x16x32_bf16 v[22:25], v[154:157], v[218:221], v[22:25]
	v_mfma_f32_16x16x32_bf16 v[18:21], v[178:181], v[218:221], v[18:21]
	v_mfma_f32_16x16x32_bf16 v[6:9], v[154:157], v[226:229], v[6:9]
	v_mfma_f32_16x16x32_bf16 v[2:5], v[178:181], v[226:229], v[2:5]
	s_setprio 0
	s_barrier
	s_add_i32 s74, 0, 0x18000
	s_add_i32 s75, 0, 0x1c000
	v_add_u32_e32 v142, s74, v196
	v_add_u32_e32 v178, s75, v196
	ds_read_b128 v[122:125], v142
	ds_read_b128 v[134:137], v142 offset:1024
	ds_read_b128 v[138:141], v142 offset:2048
	ds_read_b128 v[142:145], v142 offset:3072
	ds_read_b128 v[150:153], v178
	ds_read_b128 v[154:157], v178 offset:1024
	ds_read_b128 v[158:161], v178 offset:2048
	ds_read_b128 v[178:181], v178 offset:3072
	s_add_u32 s42, s42, s16
	s_addc_u32 s43, s43, 0
	s_mov_b32 m0, s58
	v_lshl_add_u64 v[238:239], s[42:43], 0, v[162:163]
	ds_read_b128 v[182:185], v200 offset:32768
	ds_read_b128 v[186:189], v200 offset:33792
	ds_read_b128 v[190:193], v200 offset:34816
	ds_read_b128 v[202:205], v200 offset:35840
	ds_read_b128 v[214:217], v200 offset:36864
	ds_read_b128 v[218:221], v200 offset:37888
	ds_read_b128 v[222:225], v200 offset:38912
	ds_read_b128 v[226:229], v200 offset:39936
	global_load_lds_dwordx4 v[238:239], off
	v_lshl_add_u64 v[238:239], s[42:43], 0, v[164:165]
	s_mov_b32 m0, s59
	s_nop 0
	global_load_lds_dwordx4 v[238:239], off
	s_waitcnt vmcnt(8)
	s_waitcnt lgkmcnt(0)
	s_barrier
	s_setprio 1
	s_waitcnt lgkmcnt(0)
	v_mfma_f32_16x16x32_bf16 v[130:133], v[122:125], v[182:185], v[130:133]
	v_mfma_f32_16x16x32_bf16 v[126:129], v[138:141], v[182:185], v[126:129]
	v_mfma_f32_16x16x32_bf16 v[110:113], v[122:125], v[190:193], v[110:113]
	v_mfma_f32_16x16x32_bf16 v[106:109], v[138:141], v[190:193], v[106:109]
	v_mfma_f32_16x16x32_bf16 v[94:97], v[122:125], v[214:217], v[94:97]
	v_mfma_f32_16x16x32_bf16 v[90:93], v[138:141], v[214:217], v[90:93]
	v_mfma_f32_16x16x32_bf16 v[78:81], v[122:125], v[222:225], v[78:81]
	v_mfma_f32_16x16x32_bf16 v[74:77], v[138:141], v[222:225], v[74:77]
	v_mfma_f32_16x16x32_bf16 v[130:133], v[134:137], v[186:189], v[130:133]
	v_mfma_f32_16x16x32_bf16 v[126:129], v[142:145], v[186:189], v[126:129]
	v_mfma_f32_16x16x32_bf16 v[110:113], v[134:137], v[202:205], v[110:113]
	v_mfma_f32_16x16x32_bf16 v[106:109], v[142:145], v[202:205], v[106:109]
	v_mfma_f32_16x16x32_bf16 v[94:97], v[134:137], v[218:221], v[94:97]
	v_mfma_f32_16x16x32_bf16 v[90:93], v[142:145], v[218:221], v[90:93]
	v_mfma_f32_16x16x32_bf16 v[78:81], v[134:137], v[226:229], v[78:81]
	v_mfma_f32_16x16x32_bf16 v[74:77], v[142:145], v[226:229], v[74:77]
	s_setprio 0
	s_setprio 1
	v_mfma_f32_16x16x32_bf16 v[118:121], v[150:153], v[182:185], v[118:121]
	v_mfma_f32_16x16x32_bf16 v[114:117], v[158:161], v[182:185], v[114:117]
	v_mfma_f32_16x16x32_bf16 v[102:105], v[150:153], v[190:193], v[102:105]
	v_mfma_f32_16x16x32_bf16 v[98:101], v[158:161], v[190:193], v[98:101]
	v_mfma_f32_16x16x32_bf16 v[86:89], v[150:153], v[214:217], v[86:89]
	v_mfma_f32_16x16x32_bf16 v[82:85], v[158:161], v[214:217], v[82:85]
	v_mfma_f32_16x16x32_bf16 v[70:73], v[150:153], v[222:225], v[70:73]
	v_mfma_f32_16x16x32_bf16 v[66:69], v[158:161], v[222:225], v[66:69]
	v_mfma_f32_16x16x32_bf16 v[118:121], v[154:157], v[186:189], v[118:121]
	v_mfma_f32_16x16x32_bf16 v[114:117], v[178:181], v[186:189], v[114:117]
	v_mfma_f32_16x16x32_bf16 v[102:105], v[154:157], v[202:205], v[102:105]
	v_mfma_f32_16x16x32_bf16 v[98:101], v[178:181], v[202:205], v[98:101]
	v_mfma_f32_16x16x32_bf16 v[86:89], v[154:157], v[218:221], v[86:89]
	v_mfma_f32_16x16x32_bf16 v[82:85], v[178:181], v[218:221], v[82:85]
	v_mfma_f32_16x16x32_bf16 v[70:73], v[154:157], v[226:229], v[70:73]
	v_mfma_f32_16x16x32_bf16 v[66:69], v[178:181], v[226:229], v[66:69]
	s_setprio 0
	s_barrier
	s_add_i32 s42, s74, s51
	v_lshl_add_u64 v[166:167], v[166:167], 0, s[14:15]
	s_mov_b32 m0, s42
	ds_read_b128 v[182:185], v200 offset:49152
	ds_read_b128 v[186:189], v200 offset:50176
	ds_read_b128 v[190:193], v200 offset:51200
	ds_read_b128 v[202:205], v200 offset:52224
	ds_read_b128 v[214:217], v200 offset:53248
	ds_read_b128 v[218:221], v200 offset:54272
	ds_read_b128 v[222:225], v200 offset:55296
	ds_read_b128 v[226:229], v200 offset:56320
	global_load_lds_dwordx4 v[166:167], off
	v_lshl_add_u64 v[166:167], v[194:195], 0, s[14:15]
	s_add_i32 m0, s42, 0x2000
	s_add_i32 s42, s75, s51
	global_load_lds_dwordx4 v[166:167], off
	v_lshl_add_u64 v[166:167], v[230:231], 0, s[14:15]
	s_mov_b32 m0, s42
	s_nop 0
	global_load_lds_dwordx4 v[166:167], off
	v_lshl_add_u64 v[166:167], v[232:233], 0, s[14:15]
	s_add_i32 m0, s42, 0x2000
	s_nop 0
	global_load_lds_dwordx4 v[166:167], off
	v_lshl_add_u64 v[166:167], v[234:235], 0, s[14:15]
	s_mov_b32 m0, s65
	s_nop 0
	global_load_lds_dwordx4 v[166:167], off
	v_lshl_add_u64 v[166:167], v[236:237], 0, s[14:15]
	s_mov_b32 m0, s66
	s_nop 0
	global_load_lds_dwordx4 v[166:167], off
	s_waitcnt vmcnt(8)
	s_waitcnt lgkmcnt(0)
	s_barrier
	s_setprio 1
	s_waitcnt lgkmcnt(0)
	v_mfma_f32_16x16x32_bf16 v[62:65], v[122:125], v[182:185], v[62:65]
	v_mfma_f32_16x16x32_bf16 v[58:61], v[138:141], v[182:185], v[58:61]
	v_mfma_f32_16x16x32_bf16 v[46:49], v[122:125], v[190:193], v[46:49]
	v_mfma_f32_16x16x32_bf16 v[42:45], v[138:141], v[190:193], v[42:45]
	v_mfma_f32_16x16x32_bf16 v[30:33], v[122:125], v[214:217], v[30:33]
	v_mfma_f32_16x16x32_bf16 v[26:29], v[138:141], v[214:217], v[26:29]
	v_mfma_f32_16x16x32_bf16 v[14:17], v[122:125], v[222:225], v[14:17]
	v_mfma_f32_16x16x32_bf16 v[10:13], v[138:141], v[222:225], v[10:13]
	v_mfma_f32_16x16x32_bf16 v[62:65], v[134:137], v[186:189], v[62:65]
	v_mfma_f32_16x16x32_bf16 v[58:61], v[142:145], v[186:189], v[58:61]
	v_mfma_f32_16x16x32_bf16 v[46:49], v[134:137], v[202:205], v[46:49]
	v_mfma_f32_16x16x32_bf16 v[42:45], v[142:145], v[202:205], v[42:45]
	v_mfma_f32_16x16x32_bf16 v[30:33], v[134:137], v[218:221], v[30:33]
	v_mfma_f32_16x16x32_bf16 v[26:29], v[142:145], v[218:221], v[26:29]
	v_mfma_f32_16x16x32_bf16 v[14:17], v[134:137], v[226:229], v[14:17]
	v_mfma_f32_16x16x32_bf16 v[10:13], v[142:145], v[226:229], v[10:13]
	s_setprio 0
	s_setprio 1
	v_mfma_f32_16x16x32_bf16 v[54:57], v[150:153], v[182:185], v[54:57]
	v_mfma_f32_16x16x32_bf16 v[50:53], v[158:161], v[182:185], v[50:53]
	v_mfma_f32_16x16x32_bf16 v[38:41], v[150:153], v[190:193], v[38:41]
	v_mfma_f32_16x16x32_bf16 v[34:37], v[158:161], v[190:193], v[34:37]
	v_mfma_f32_16x16x32_bf16 v[22:25], v[150:153], v[214:217], v[22:25]
	v_mfma_f32_16x16x32_bf16 v[18:21], v[158:161], v[214:217], v[18:21]
	v_mfma_f32_16x16x32_bf16 v[6:9], v[150:153], v[222:225], v[6:9]
	v_mfma_f32_16x16x32_bf16 v[2:5], v[158:161], v[222:225], v[2:5]
	v_mfma_f32_16x16x32_bf16 v[54:57], v[154:157], v[186:189], v[54:57]
	v_mfma_f32_16x16x32_bf16 v[50:53], v[178:181], v[186:189], v[50:53]
	v_mfma_f32_16x16x32_bf16 v[38:41], v[154:157], v[202:205], v[38:41]
	v_mfma_f32_16x16x32_bf16 v[34:37], v[178:181], v[202:205], v[34:37]
	v_mfma_f32_16x16x32_bf16 v[22:25], v[154:157], v[218:221], v[22:25]
	v_mfma_f32_16x16x32_bf16 v[18:21], v[178:181], v[218:221], v[18:21]
	v_mfma_f32_16x16x32_bf16 v[6:9], v[154:157], v[226:229], v[6:9]
	v_mfma_f32_16x16x32_bf16 v[2:5], v[178:181], v[226:229], v[2:5]
	s_setprio 0
	s_barrier
	s_add_u32 s40, s40, 0x100
	s_addc_u32 s41, s41, 0
	s_add_u32 s34, s34, 0x100
	s_addc_u32 s48, s48, 0
	s_cmp_ge_u32 s49, s64
	s_mov_b32 s42, s49
	s_cbranch_scc0 .LBB0_374
	s_and_b64 vcc, exec, s[22:23]
	s_cbranch_vccz .LBB0_377
	s_barrier

.LBB0_473:
	s_and_b64 vcc, exec, s[38:39]
	s_mov_b64 s[38:39], -1
	s_cbranch_vccnz .LBB0_366
	s_andn2_b64 vcc, exec, s[6:7]
	s_cbranch_vccnz .LBB0_365
	s_branch .LBB0_365

.LBB0_510:
	s_ashr_i32 s31, s30, 31
	s_lshl_b64 s[38:39], s[30:31], 19
	s_add_u32 s38, s20, s38
	s_addc_u32 s39, s21, s39
	s_and_b64 s[40:41], s[36:37], exec
	s_cselect_b32 s16, s39, s45
	s_cselect_b32 s29, s38, s44
	s_ashr_i32 s23, s22, 31
	s_lshl_b64 s[40:41], s[22:23], 19
	s_add_u32 s40, s26, s40
	s_addc_u32 s41, s27, s41
	s_and_b64 s[48:49], s[36:37], exec
	s_cselect_b32 s23, s41, s47
	s_cselect_b32 s31, s40, s46
	s_add_u32 s44, s44, 0x40080
	s_addc_u32 s45, s45, 0
	s_add_u32 s34, s46, 0x100
	v_mov_b32_e32 v2, 0
	s_addc_u32 s43, s47, 0
	s_mov_b32 s50, -2
	v_mov_b32_e32 v3, v2
	v_mov_b32_e32 v4, v2
	v_mov_b32_e32 v5, v2
	v_mov_b32_e32 v6, v2
	v_mov_b32_e32 v7, v2
	v_mov_b32_e32 v8, v2
	v_mov_b32_e32 v9, v2
	v_mov_b32_e32 v18, v2
	v_mov_b32_e32 v19, v2
	v_mov_b32_e32 v20, v2
	v_mov_b32_e32 v21, v2
	v_mov_b32_e32 v22, v2
	v_mov_b32_e32 v23, v2
	v_mov_b32_e32 v24, v2
	v_mov_b32_e32 v25, v2
	v_mov_b32_e32 v34, v2
	v_mov_b32_e32 v35, v2
	v_mov_b32_e32 v36, v2
	v_mov_b32_e32 v37, v2
	v_mov_b32_e32 v38, v2
	v_mov_b32_e32 v39, v2
	v_mov_b32_e32 v40, v2
	v_mov_b32_e32 v41, v2
	v_mov_b32_e32 v58, v2
	v_mov_b32_e32 v59, v2
	v_mov_b32_e32 v60, v2
	v_mov_b32_e32 v61, v2
	v_mov_b32_e32 v62, v2
	v_mov_b32_e32 v63, v2
	v_mov_b32_e32 v64, v2
	v_mov_b32_e32 v65, v2
	v_mov_b32_e32 v10, v2
	v_mov_b32_e32 v11, v2
	v_mov_b32_e32 v12, v2
	v_mov_b32_e32 v13, v2
	v_mov_b32_e32 v14, v2
	v_mov_b32_e32 v15, v2
	v_mov_b32_e32 v16, v2
	v_mov_b32_e32 v17, v2
	v_mov_b32_e32 v26, v2
	v_mov_b32_e32 v27, v2
	v_mov_b32_e32 v28, v2
	v_mov_b32_e32 v29, v2
	v_mov_b32_e32 v30, v2
	v_mov_b32_e32 v31, v2
	v_mov_b32_e32 v32, v2
	v_mov_b32_e32 v33, v2
	v_mov_b32_e32 v42, v2
	v_mov_b32_e32 v43, v2
	v_mov_b32_e32 v44, v2
	v_mov_b32_e32 v45, v2
	v_mov_b32_e32 v46, v2
	v_mov_b32_e32 v47, v2
	v_mov_b32_e32 v48, v2
	v_mov_b32_e32 v49, v2
	v_mov_b32_e32 v74, v2
	v_mov_b32_e32 v75, v2
	v_mov_b32_e32 v76, v2
	v_mov_b32_e32 v77, v2
	v_mov_b32_e32 v78, v2
	v_mov_b32_e32 v79, v2
	v_mov_b32_e32 v80, v2
	v_mov_b32_e32 v81, v2
	v_mov_b32_e32 v82, v2
	v_mov_b32_e32 v83, v2
	v_mov_b32_e32 v84, v2
	v_mov_b32_e32 v85, v2
	v_mov_b32_e32 v86, v2
	v_mov_b32_e32 v87, v2
	v_mov_b32_e32 v88, v2
	v_mov_b32_e32 v89, v2
	v_mov_b32_e32 v98, v2
	v_mov_b32_e32 v99, v2
	v_mov_b32_e32 v100, v2
	v_mov_b32_e32 v101, v2
	v_mov_b32_e32 v102, v2
	v_mov_b32_e32 v103, v2
	v_mov_b32_e32 v104, v2
	v_mov_b32_e32 v105, v2
	v_mov_b32_e32 v114, v2
	v_mov_b32_e32 v115, v2
	v_mov_b32_e32 v116, v2
	v_mov_b32_e32 v117, v2
	v_mov_b32_e32 v118, v2
	v_mov_b32_e32 v119, v2
	v_mov_b32_e32 v120, v2
	v_mov_b32_e32 v121, v2
	v_mov_b32_e32 v130, v2
	v_mov_b32_e32 v131, v2
	v_mov_b32_e32 v132, v2
	v_mov_b32_e32 v133, v2
	v_mov_b32_e32 v134, v2
	v_mov_b32_e32 v135, v2
	v_mov_b32_e32 v136, v2
	v_mov_b32_e32 v137, v2
	v_mov_b32_e32 v90, v2
	v_mov_b32_e32 v91, v2
	v_mov_b32_e32 v92, v2
	v_mov_b32_e32 v93, v2
	v_mov_b32_e32 v94, v2
	v_mov_b32_e32 v95, v2
	v_mov_b32_e32 v96, v2
	v_mov_b32_e32 v97, v2
	v_mov_b32_e32 v106, v2
	v_mov_b32_e32 v107, v2
	v_mov_b32_e32 v108, v2
	v_mov_b32_e32 v109, v2
	v_mov_b32_e32 v110, v2
	v_mov_b32_e32 v111, v2
	v_mov_b32_e32 v112, v2
	v_mov_b32_e32 v113, v2
	v_mov_b32_e32 v122, v2
	v_mov_b32_e32 v123, v2
	v_mov_b32_e32 v124, v2
	v_mov_b32_e32 v125, v2
	v_mov_b32_e32 v126, v2
	v_mov_b32_e32 v127, v2
	v_mov_b32_e32 v128, v2
	v_mov_b32_e32 v129, v2
	v_mov_b32_e32 v138, v2
	v_mov_b32_e32 v139, v2
	v_mov_b32_e32 v140, v2
	v_mov_b32_e32 v141, v2
	v_mov_b32_e32 v142, v2
	v_mov_b32_e32 v143, v2
	v_mov_b32_e32 v144, v2
	v_mov_b32_e32 v145, v2
	s_cmp_eq_u32 s3, 0
	s_cbranch_scc1 .Ltb_sw_skip
	s_cmp_eq_u32 s6, 0
	s_cbranch_scc1 .Ltb_sw_skip
	s_barrier
.Ltb_sw_skip:
.LBB0_511:
	s_add_u32 s46, s44, 0xfffc0080
	s_addc_u32 s47, s45, -1
	s_add_i32 s51, 0, 0x10000
	s_cmp_eq_u32 s50, 12
	s_cselect_b32 s49, s16, s47
	s_cselect_b32 s48, s29, s46
	v_add_u32_e32 v0, s51, v198
	s_cselect_b32 s47, s23, s43
	s_cselect_b32 s46, s31, s34
	s_add_i32 s65, 0, 0x14000
	ds_read_b128 v[50:53], v0
	ds_read_b128 v[54:57], v0 offset:1024
	ds_read_b128 v[66:69], v0 offset:2048
	ds_read_b128 v[70:73], v0 offset:3072
	v_add_u32_e32 v0, s65, v198
	ds_read_b128 v[174:177], v0
	ds_read_b128 v[178:181], v0 offset:1024
	ds_read_b128 v[182:185], v0 offset:2048
	ds_read_b128 v[186:189], v0 offset:3072
	v_lshl_add_u64 v[166:167], s[44:45], 0, v[164:165]
	s_add_i32 m0, s52, 0xc000
	ds_read_b128 v[190:193], v203
	ds_read_b128 v[194:197], v203 offset:1024
	ds_read_b128 v[214:217], v203 offset:2048
	ds_read_b128 v[218:221], v203 offset:3072
	ds_read_b128 v[222:225], v203 offset:4096
	ds_read_b128 v[226:229], v203 offset:5120
	ds_read_b128 v[230:233], v203 offset:6144
	ds_read_b128 v[234:237], v203 offset:7168
	global_load_lds_dwordx4 v[166:167], off
	v_lshl_add_u64 v[166:167], s[44:45], 0, v[172:173]
	s_add_i32 m0, s52, 0xe000
	s_nop 0
	global_load_lds_dwordx4 v[166:167], off
	s_waitcnt vmcnt(8)
	s_waitcnt lgkmcnt(0)
	s_barrier
	s_setprio 1
	s_waitcnt lgkmcnt(0)
	v_mfma_f32_16x16x32_bf16 v[142:145], v[50:53], v[190:193], v[142:145]
	v_mfma_f32_16x16x32_bf16 v[138:141], v[66:69], v[190:193], v[138:141]
	v_mfma_f32_16x16x32_bf16 v[126:129], v[50:53], v[214:217], v[126:129]
	v_mfma_f32_16x16x32_bf16 v[122:125], v[66:69], v[214:217], v[122:125]
	v_mfma_f32_16x16x32_bf16 v[110:113], v[50:53], v[222:225], v[110:113]
	v_mfma_f32_16x16x32_bf16 v[106:109], v[66:69], v[222:225], v[106:109]
	v_mfma_f32_16x16x32_bf16 v[94:97], v[50:53], v[230:233], v[94:97]
	v_mfma_f32_16x16x32_bf16 v[90:93], v[66:69], v[230:233], v[90:93]
	v_mfma_f32_16x16x32_bf16 v[142:145], v[54:57], v[194:197], v[142:145]
	v_mfma_f32_16x16x32_bf16 v[138:141], v[70:73], v[194:197], v[138:141]
	v_mfma_f32_16x16x32_bf16 v[126:129], v[54:57], v[218:221], v[126:129]
	v_mfma_f32_16x16x32_bf16 v[122:125], v[70:73], v[218:221], v[122:125]
	v_mfma_f32_16x16x32_bf16 v[110:113], v[54:57], v[226:229], v[110:113]
	v_mfma_f32_16x16x32_bf16 v[106:109], v[70:73], v[226:229], v[106:109]
	v_mfma_f32_16x16x32_bf16 v[94:97], v[54:57], v[234:237], v[94:97]
	v_mfma_f32_16x16x32_bf16 v[90:93], v[70:73], v[234:237], v[90:93]
	s_setprio 0
	s_setprio 1
	v_mfma_f32_16x16x32_bf16 v[134:137], v[174:177], v[190:193], v[134:137]
	v_mfma_f32_16x16x32_bf16 v[130:133], v[182:185], v[190:193], v[130:133]
	v_mfma_f32_16x16x32_bf16 v[118:121], v[174:177], v[214:217], v[118:121]
	v_mfma_f32_16x16x32_bf16 v[114:117], v[182:185], v[214:217], v[114:117]
	v_mfma_f32_16x16x32_bf16 v[102:105], v[174:177], v[222:225], v[102:105]
	v_mfma_f32_16x16x32_bf16 v[98:101], v[182:185], v[222:225], v[98:101]
	v_mfma_f32_16x16x32_bf16 v[86:89], v[174:177], v[230:233], v[86:89]
	v_mfma_f32_16x16x32_bf16 v[82:85], v[182:185], v[230:233], v[82:85]
	v_mfma_f32_16x16x32_bf16 v[134:137], v[178:181], v[194:197], v[134:137]
	v_mfma_f32_16x16x32_bf16 v[130:133], v[186:189], v[194:197], v[130:133]
	v_mfma_f32_16x16x32_bf16 v[118:121], v[178:181], v[218:221], v[118:121]
	v_mfma_f32_16x16x32_bf16 v[114:117], v[186:189], v[218:221], v[114:117]
	v_mfma_f32_16x16x32_bf16 v[102:105], v[178:181], v[226:229], v[102:105]
	v_mfma_f32_16x16x32_bf16 v[98:101], v[186:189], v[226:229], v[98:101]
	v_mfma_f32_16x16x32_bf16 v[86:89], v[178:181], v[234:237], v[86:89]
	v_mfma_f32_16x16x32_bf16 v[82:85], v[186:189], v[234:237], v[82:85]
	s_setprio 0
	s_barrier
	s_add_i32 s51, s51, s12
	v_lshl_add_u64 v[166:167], s[46:47], 0, v[152:153]
	s_mov_b32 m0, s51
	ds_read_b128 v[190:193], v203 offset:16384
	ds_read_b128 v[194:197], v203 offset:17408
	ds_read_b128 v[214:217], v203 offset:18432
	ds_read_b128 v[218:221], v203 offset:19456
	ds_read_b128 v[222:225], v203 offset:20480
	ds_read_b128 v[226:229], v203 offset:21504
	ds_read_b128 v[230:233], v203 offset:22528
	ds_read_b128 v[234:237], v203 offset:23552
	global_load_lds_dwordx4 v[166:167], off
	s_add_i32 m0, s51, 0x2000
	s_add_u32 s66, s46, 0x40000
	v_lshl_add_u64 v[204:205], s[46:47], 0, v[156:157]
	s_addc_u32 s67, s47, 0
	s_add_i32 s51, s65, s12
	global_load_lds_dwordx4 v[204:205], off
	v_lshl_add_u64 v[238:239], s[66:67], 0, v[152:153]
	s_mov_b32 m0, s51
	v_lshl_add_u64 v[240:241], s[48:49], 0, v[154:155]
	global_load_lds_dwordx4 v[238:239], off
	v_lshl_add_u64 v[238:239], s[66:67], 0, v[156:157]
	s_add_i32 m0, s51, 0x2000
	s_nop 0
	global_load_lds_dwordx4 v[238:239], off
	v_lshl_add_u64 v[238:239], s[48:49], 0, v[150:151]
	s_mov_b32 m0, s52
	s_nop 0
	global_load_lds_dwordx4 v[238:239], off
	s_mov_b32 m0, s53
	s_nop 0
	global_load_lds_dwordx4 v[240:241], off
	s_waitcnt vmcnt(8)
	s_waitcnt lgkmcnt(0)
	s_barrier
	s_setprio 1
	s_waitcnt lgkmcnt(0)
	v_mfma_f32_16x16x32_bf16 v[78:81], v[50:53], v[190:193], v[78:81]
	v_mfma_f32_16x16x32_bf16 v[74:77], v[66:69], v[190:193], v[74:77]
	v_mfma_f32_16x16x32_bf16 v[46:49], v[50:53], v[214:217], v[46:49]
	v_mfma_f32_16x16x32_bf16 v[42:45], v[66:69], v[214:217], v[42:45]
	v_mfma_f32_16x16x32_bf16 v[30:33], v[50:53], v[222:225], v[30:33]
	v_mfma_f32_16x16x32_bf16 v[26:29], v[66:69], v[222:225], v[26:29]
	v_mfma_f32_16x16x32_bf16 v[14:17], v[50:53], v[230:233], v[14:17]
	v_mfma_f32_16x16x32_bf16 v[10:13], v[66:69], v[230:233], v[10:13]
	v_mfma_f32_16x16x32_bf16 v[78:81], v[54:57], v[194:197], v[78:81]
	v_mfma_f32_16x16x32_bf16 v[74:77], v[70:73], v[194:197], v[74:77]
	v_mfma_f32_16x16x32_bf16 v[46:49], v[54:57], v[218:221], v[46:49]
	v_mfma_f32_16x16x32_bf16 v[42:45], v[70:73], v[218:221], v[42:45]
	v_mfma_f32_16x16x32_bf16 v[30:33], v[54:57], v[226:229], v[30:33]
	v_mfma_f32_16x16x32_bf16 v[26:29], v[70:73], v[226:229], v[26:29]
	v_mfma_f32_16x16x32_bf16 v[14:17], v[54:57], v[234:237], v[14:17]
	v_mfma_f32_16x16x32_bf16 v[10:13], v[70:73], v[234:237], v[10:13]
	s_setprio 0
	s_setprio 1
	v_mfma_f32_16x16x32_bf16 v[38:41], v[174:177], v[214:217], v[38:41]
	v_mfma_f32_16x16x32_bf16 v[34:37], v[182:185], v[214:217], v[34:37]
	v_mfma_f32_16x16x32_bf16 v[22:25], v[174:177], v[222:225], v[22:25]
	v_mfma_f32_16x16x32_bf16 v[18:21], v[182:185], v[222:225], v[18:21]
	v_mfma_f32_16x16x32_bf16 v[6:9], v[174:177], v[230:233], v[6:9]
	v_mfma_f32_16x16x32_bf16 v[2:5], v[182:185], v[230:233], v[2:5]
	v_mfma_f32_16x16x32_bf16 v[50:53], v[174:177], v[190:193], v[62:65]
	v_mfma_f32_16x16x32_bf16 v[54:57], v[182:185], v[190:193], v[58:61]
	v_mfma_f32_16x16x32_bf16 v[38:41], v[178:181], v[218:221], v[38:41]
	v_mfma_f32_16x16x32_bf16 v[34:37], v[186:189], v[218:221], v[34:37]
	v_mfma_f32_16x16x32_bf16 v[22:25], v[178:181], v[226:229], v[22:25]
	v_mfma_f32_16x16x32_bf16 v[18:21], v[186:189], v[226:229], v[18:21]
	v_mfma_f32_16x16x32_bf16 v[6:9], v[178:181], v[234:237], v[6:9]
	v_mfma_f32_16x16x32_bf16 v[2:5], v[186:189], v[234:237], v[2:5]
	v_mfma_f32_16x16x32_bf16 v[50:53], v[178:181], v[194:197], v[50:53]
	v_mfma_f32_16x16x32_bf16 v[54:57], v[186:189], v[194:197], v[54:57]
	s_setprio 0
	s_barrier
	s_add_i32 s51, 0, 0x18000
	v_add_u32_e32 v0, s51, v198
	s_add_i32 s65, 0, 0x1c000
	ds_read_b128 v[58:61], v0
	ds_read_b128 v[62:65], v0 offset:1024
	ds_read_b128 v[66:69], v0 offset:2048
	ds_read_b128 v[70:73], v0 offset:3072
	v_add_u32_e32 v0, s65, v198
	ds_read_b128 v[174:177], v0
	ds_read_b128 v[178:181], v0 offset:1024
	ds_read_b128 v[182:185], v0 offset:2048
	ds_read_b128 v[186:189], v0 offset:3072
	s_add_u32 s48, s48, 0x40000
	s_addc_u32 s49, s49, 0
	s_mov_b32 m0, s54
	v_lshl_add_u64 v[242:243], s[48:49], 0, v[150:151]
	ds_read_b128 v[190:193], v203 offset:32768
	ds_read_b128 v[194:197], v203 offset:33792
	ds_read_b128 v[214:217], v203 offset:34816
	ds_read_b128 v[218:221], v203 offset:35840
	ds_read_b128 v[222:225], v203 offset:36864
	ds_read_b128 v[226:229], v203 offset:37888
	ds_read_b128 v[230:233], v203 offset:38912
	ds_read_b128 v[234:237], v203 offset:39936
	global_load_lds_dwordx4 v[242:243], off
	v_lshl_add_u64 v[242:243], s[48:49], 0, v[154:155]
	s_mov_b32 m0, s55
	s_nop 0
	global_load_lds_dwordx4 v[242:243], off
	s_waitcnt vmcnt(8)
	s_waitcnt lgkmcnt(0)
	s_barrier
	s_setprio 1
	s_waitcnt lgkmcnt(0)
	v_mfma_f32_16x16x32_bf16 v[142:145], v[58:61], v[190:193], v[142:145]
	v_mfma_f32_16x16x32_bf16 v[138:141], v[66:69], v[190:193], v[138:141]
	v_mfma_f32_16x16x32_bf16 v[126:129], v[58:61], v[214:217], v[126:129]
	v_mfma_f32_16x16x32_bf16 v[122:125], v[66:69], v[214:217], v[122:125]
	v_mfma_f32_16x16x32_bf16 v[110:113], v[58:61], v[222:225], v[110:113]
	v_mfma_f32_16x16x32_bf16 v[106:109], v[66:69], v[222:225], v[106:109]
	v_mfma_f32_16x16x32_bf16 v[94:97], v[58:61], v[230:233], v[94:97]
	v_mfma_f32_16x16x32_bf16 v[90:93], v[66:69], v[230:233], v[90:93]
	v_mfma_f32_16x16x32_bf16 v[142:145], v[62:65], v[194:197], v[142:145]
	v_mfma_f32_16x16x32_bf16 v[138:141], v[70:73], v[194:197], v[138:141]
	v_mfma_f32_16x16x32_bf16 v[126:129], v[62:65], v[218:221], v[126:129]
	v_mfma_f32_16x16x32_bf16 v[122:125], v[70:73], v[218:221], v[122:125]
	v_mfma_f32_16x16x32_bf16 v[110:113], v[62:65], v[226:229], v[110:113]
	v_mfma_f32_16x16x32_bf16 v[106:109], v[70:73], v[226:229], v[106:109]
	v_mfma_f32_16x16x32_bf16 v[94:97], v[62:65], v[234:237], v[94:97]
	v_mfma_f32_16x16x32_bf16 v[90:93], v[70:73], v[234:237], v[90:93]
	s_setprio 0
	s_setprio 1
	v_mfma_f32_16x16x32_bf16 v[134:137], v[174:177], v[190:193], v[134:137]
	v_mfma_f32_16x16x32_bf16 v[130:133], v[182:185], v[190:193], v[130:133]
	v_mfma_f32_16x16x32_bf16 v[118:121], v[174:177], v[214:217], v[118:121]
	v_mfma_f32_16x16x32_bf16 v[114:117], v[182:185], v[214:217], v[114:117]
	v_mfma_f32_16x16x32_bf16 v[102:105], v[174:177], v[222:225], v[102:105]
	v_mfma_f32_16x16x32_bf16 v[98:101], v[182:185], v[222:225], v[98:101]
	v_mfma_f32_16x16x32_bf16 v[86:89], v[174:177], v[230:233], v[86:89]
	v_mfma_f32_16x16x32_bf16 v[82:85], v[182:185], v[230:233], v[82:85]
	v_mfma_f32_16x16x32_bf16 v[134:137], v[178:181], v[194:197], v[134:137]
	v_mfma_f32_16x16x32_bf16 v[130:133], v[186:189], v[194:197], v[130:133]
	v_mfma_f32_16x16x32_bf16 v[118:121], v[178:181], v[218:221], v[118:121]
	v_mfma_f32_16x16x32_bf16 v[114:117], v[186:189], v[218:221], v[114:117]
	v_mfma_f32_16x16x32_bf16 v[102:105], v[178:181], v[226:229], v[102:105]
	v_mfma_f32_16x16x32_bf16 v[98:101], v[186:189], v[226:229], v[98:101]
	v_mfma_f32_16x16x32_bf16 v[86:89], v[178:181], v[234:237], v[86:89]
	v_mfma_f32_16x16x32_bf16 v[82:85], v[186:189], v[234:237], v[82:85]
	s_setprio 0
	s_barrier
	s_add_i32 s48, s51, s12
	v_lshl_add_u64 v[166:167], v[166:167], 0, s[14:15]
	s_mov_b32 m0, s48
	ds_read_b128 v[190:193], v203 offset:49152
	ds_read_b128 v[194:197], v203 offset:50176
	ds_read_b128 v[214:217], v203 offset:51200
	ds_read_b128 v[218:221], v203 offset:52224
	ds_read_b128 v[222:225], v203 offset:53248
	ds_read_b128 v[226:229], v203 offset:54272
	ds_read_b128 v[230:233], v203 offset:55296
	ds_read_b128 v[234:237], v203 offset:56320
	global_load_lds_dwordx4 v[166:167], off
	s_add_i32 m0, s48, 0x2000
	s_add_u32 s46, s46, 0x40080
	v_lshl_add_u64 v[166:167], v[204:205], 0, s[14:15]
	s_addc_u32 s47, s47, 0
	s_add_i32 s48, s65, s12
	global_load_lds_dwordx4 v[166:167], off
	v_lshl_add_u64 v[166:167], s[46:47], 0, v[152:153]
	s_mov_b32 m0, s48
	s_nop 0
	global_load_lds_dwordx4 v[166:167], off
	v_lshl_add_u64 v[166:167], s[46:47], 0, v[156:157]
	s_add_i32 m0, s48, 0x2000
	s_nop 0
	global_load_lds_dwordx4 v[166:167], off
	v_lshl_add_u64 v[166:167], v[238:239], 0, s[14:15]
	s_mov_b32 m0, s59
	s_nop 0
	global_load_lds_dwordx4 v[166:167], off
	v_lshl_add_u64 v[166:167], v[240:241], 0, s[14:15]
	s_mov_b32 m0, s60
	s_nop 0
	global_load_lds_dwordx4 v[166:167], off
	s_waitcnt vmcnt(8)
	s_waitcnt lgkmcnt(0)
	s_barrier
	s_setprio 1
	s_waitcnt lgkmcnt(0)
	v_mfma_f32_16x16x32_bf16 v[78:81], v[58:61], v[190:193], v[78:81]
	v_mfma_f32_16x16x32_bf16 v[74:77], v[66:69], v[190:193], v[74:77]
	v_mfma_f32_16x16x32_bf16 v[46:49], v[58:61], v[214:217], v[46:49]
	v_mfma_f32_16x16x32_bf16 v[42:45], v[66:69], v[214:217], v[42:45]
	v_mfma_f32_16x16x32_bf16 v[30:33], v[58:61], v[222:225], v[30:33]
	v_mfma_f32_16x16x32_bf16 v[26:29], v[66:69], v[222:225], v[26:29]
	v_mfma_f32_16x16x32_bf16 v[14:17], v[58:61], v[230:233], v[14:17]
	v_mfma_f32_16x16x32_bf16 v[10:13], v[66:69], v[230:233], v[10:13]
	v_mfma_f32_16x16x32_bf16 v[78:81], v[62:65], v[194:197], v[78:81]
	v_mfma_f32_16x16x32_bf16 v[74:77], v[70:73], v[194:197], v[74:77]
	v_mfma_f32_16x16x32_bf16 v[46:49], v[62:65], v[218:221], v[46:49]
	v_mfma_f32_16x16x32_bf16 v[42:45], v[70:73], v[218:221], v[42:45]
	v_mfma_f32_16x16x32_bf16 v[30:33], v[62:65], v[226:229], v[30:33]
	v_mfma_f32_16x16x32_bf16 v[26:29], v[70:73], v[226:229], v[26:29]
	v_mfma_f32_16x16x32_bf16 v[14:17], v[62:65], v[234:237], v[14:17]
	v_mfma_f32_16x16x32_bf16 v[10:13], v[70:73], v[234:237], v[10:13]
	s_setprio 0
	s_setprio 1
	v_mfma_f32_16x16x32_bf16 v[50:53], v[174:177], v[190:193], v[50:53]
	v_mfma_f32_16x16x32_bf16 v[62:65], v[178:181], v[194:197], v[50:53]
	v_mfma_f32_16x16x32_bf16 v[50:53], v[182:185], v[190:193], v[54:57]
	v_mfma_f32_16x16x32_bf16 v[38:41], v[174:177], v[214:217], v[38:41]
	v_mfma_f32_16x16x32_bf16 v[34:37], v[182:185], v[214:217], v[34:37]
	v_mfma_f32_16x16x32_bf16 v[22:25], v[174:177], v[222:225], v[22:25]
	v_mfma_f32_16x16x32_bf16 v[18:21], v[182:185], v[222:225], v[18:21]
	v_mfma_f32_16x16x32_bf16 v[6:9], v[174:177], v[230:233], v[6:9]
	v_mfma_f32_16x16x32_bf16 v[2:5], v[182:185], v[230:233], v[2:5]
	v_mfma_f32_16x16x32_bf16 v[58:61], v[186:189], v[194:197], v[50:53]
	v_mfma_f32_16x16x32_bf16 v[38:41], v[178:181], v[218:221], v[38:41]
	v_mfma_f32_16x16x32_bf16 v[34:37], v[186:189], v[218:221], v[34:37]
	v_mfma_f32_16x16x32_bf16 v[22:25], v[178:181], v[226:229], v[22:25]
	v_mfma_f32_16x16x32_bf16 v[18:21], v[186:189], v[226:229], v[18:21]
	v_mfma_f32_16x16x32_bf16 v[6:9], v[178:181], v[234:237], v[6:9]
	v_mfma_f32_16x16x32_bf16 v[2:5], v[186:189], v[234:237], v[2:5]
	s_setprio 0
	s_barrier
	s_add_i32 s50, s50, 2
	s_add_u32 s44, s44, 0x100
	s_addc_u32 s45, s45, 0
	s_add_u32 s34, s34, 0x100
	s_addc_u32 s43, s43, 0
	s_cmp_gt_u32 s50, 13
	s_cbranch_scc0 .LBB0_511
	s_and_b64 vcc, exec, s[8:9]
	s_cbranch_vccz .LBB0_514
	s_barrier

.LBB0_610:
	s_or_b64 exec, exec, s[2:3]
	s_andn2_b64 vcc, exec, s[36:37]
	s_mov_b64 s[2:3], -1
	s_cbranch_vccnz .LBB0_503
	s_andn2_b64 vcc, exec, s[6:7]
	s_cbranch_vccnz .LBB0_502
	s_branch .LBB0_502

.LBB0_901:
	s_mov_b32 s26, 0
	s_cbranch_execz .LBB0_904
	s_lshl_b32 s2, s16, 3
	s_add_i32 s2, s2, s12
	s_ashr_i32 s2, s2, 3
	s_add_i32 s2, s2, s20
	s_lshl_b32 s4, s2, 6
	s_ashr_i32 s3, s2, 31
	s_ashr_i32 s5, s4, 31
	s_lshl_b64 s[2:3], s[2:3], 2
	s_add_u32 s2, s22, s2
	s_addc_u32 s3, s23, s3
	global_load_dword v228, v1, s[2:3]
	v_lshl_add_u64 v[2:3], v[186:187], 0, s[4:5]
	v_sub_co_u32_e32 v198, vcc, v2, v196
	s_mov_b32 s34, 4
	s_nop 0
	v_subb_co_u32_e32 v199, vcc, v3, v197, vcc
	s_mov_b64 s[2:3], 0
	s_or_b64 s[18:19], s[18:19], exec
	s_mov_b32 s26, s13
	v_mov_b32_e32 v67, v204
	v_mov_b32_e32 v66, v203
	s_mul_i32 s29, s21, 0x90
	s_branch .LBB0_905

.LBB0_915:
	s_andn2_b64 vcc, exec, s[4:5]
	s_cbranch_vccnz .LBB0_917
	v_add3_u32 v86, s27, v188, v205
	ds_read_b128 v[2:5], v86
	ds_read_b128 v[6:9], v86 offset:32
	s_waitcnt vmcnt(3) lgkmcnt(1)
	v_mfma_f32_32x32x16_bf16 v[34:49], v[2:5], v[162:165], 0
	ds_read_b128 v[2:5], v86 offset:64
	ds_read_b128 v[82:85], v86 offset:18464
	s_waitcnt vmcnt(2) lgkmcnt(2)
	v_mfma_f32_32x32x16_bf16 v[34:49], v[6:9], v[158:161], v[34:49]
	s_waitcnt vmcnt(1) lgkmcnt(1)
	v_mfma_f32_32x32x16_bf16 v[34:49], v[2:5], v[154:157], v[34:49]
	ds_read_b128 v[2:5], v86 offset:96
	s_waitcnt vmcnt(0) lgkmcnt(0)
	v_mfma_f32_32x32x16_bf16 v[34:49], v[2:5], v[150:153], v[34:49]
	v_mul_f32_e32 v228, 0x3fb8aa3b, v228
	ds_read_b128 v[2:5], v86 offset:4608
	s_waitcnt lgkmcnt(0)
	v_mfma_f32_32x32x16_bf16 v[18:33], v[2:5], v[162:165], 0
	ds_read_b128 v[2:5], v86 offset:4640
	s_waitcnt lgkmcnt(0)
	v_mfma_f32_32x32x16_bf16 v[18:33], v[2:5], v[158:161], v[18:33]
	ds_read_b128 v[2:5], v86 offset:4672
	s_waitcnt lgkmcnt(0)
	v_mfma_f32_32x32x16_bf16 v[18:33], v[2:5], v[154:157], v[18:33]
	ds_read_b128 v[2:5], v86 offset:4704
	s_waitcnt lgkmcnt(0)
	v_mfma_f32_32x32x16_bf16 v[18:33], v[2:5], v[150:153], v[18:33]
	ds_read_b128 v[2:5], v86 offset:9216
	s_waitcnt lgkmcnt(0)
	v_mfma_f32_32x32x16_bf16 v[50:65], v[2:5], v[162:165], 0
	ds_read_b128 v[2:5], v86 offset:9248
	s_waitcnt lgkmcnt(0)
	v_mfma_f32_32x32x16_bf16 v[50:65], v[2:5], v[158:161], v[50:65]
	ds_read_b128 v[2:5], v86 offset:9280
	s_waitcnt lgkmcnt(0)
	v_mfma_f32_32x32x16_bf16 v[50:65], v[2:5], v[154:157], v[50:65]
	ds_read_b128 v[2:5], v86 offset:9312
	s_waitcnt lgkmcnt(0)
	v_mfma_f32_32x32x16_bf16 v[50:65], v[2:5], v[150:153], v[50:65]
	ds_read_b128 v[2:5], v86 offset:13824
	s_waitcnt lgkmcnt(0)
	v_mfma_f32_32x32x16_bf16 v[66:81], v[2:5], v[162:165], 0
	ds_read_b128 v[2:5], v86 offset:13856
	s_waitcnt lgkmcnt(0)
	v_mfma_f32_32x32x16_bf16 v[66:81], v[2:5], v[158:161], v[66:81]
	ds_read_b128 v[2:5], v86 offset:13888
	s_waitcnt lgkmcnt(0)
	v_mfma_f32_32x32x16_bf16 v[66:81], v[2:5], v[154:157], v[66:81]
	ds_read_b128 v[2:5], v86 offset:13920
	s_waitcnt lgkmcnt(0)
	v_mfma_f32_32x32x16_bf16 v[66:81], v[2:5], v[150:153], v[66:81]
	ds_read_b128 v[2:5], v86 offset:18432
	s_waitcnt lgkmcnt(0)
	v_mfma_f32_32x32x16_bf16 v[2:17], v[2:5], v[162:165], 0
	v_mfma_f32_32x32x16_bf16 v[2:17], v[82:85], v[158:161], v[2:17]
	ds_read_b128 v[82:85], v86 offset:18496
	s_waitcnt lgkmcnt(0)
	v_mfma_f32_32x32x16_bf16 v[2:17], v[82:85], v[154:157], v[2:17]
	ds_read_b128 v[82:85], v86 offset:18528
	s_waitcnt lgkmcnt(0)
	v_mfma_f32_32x32x16_bf16 v[2:17], v[82:85], v[150:153], v[2:17]
	s_cmp_gt_i32 s26, 0
	s_cselect_b64 vcc, -1, 0
	s_or_b64 s[2:3], s[42:43], vcc
	v_cndmask_b32_e64 v99, v35, v213, s[2:3]
	v_cndmask_b32_e32 v35, v36, v213, vcc
	v_cndmask_b32_e64 v100, v213, v35, s[44:45]
	v_cndmask_b32_e32 v35, v37, v213, vcc
	v_cndmask_b32_e64 v101, v213, v35, s[46:47]
	v_cndmask_b32_e32 v35, v38, v213, vcc
	v_cndmask_b32_e64 v102, v213, v35, s[48:49]
	v_cndmask_b32_e32 v35, v39, v213, vcc
	v_cndmask_b32_e64 v103, v213, v35, s[50:51]
	v_cndmask_b32_e32 v35, v40, v213, vcc
	v_cndmask_b32_e64 v104, v213, v35, s[52:53]
	v_cndmask_b32_e32 v35, v41, v213, vcc
	v_cndmask_b32_e32 v34, v34, v213, vcc
	v_cndmask_b32_e64 v105, v213, v35, s[54:55]
	v_cndmask_b32_e32 v35, v42, v213, vcc
	v_cndmask_b32_e64 v98, v213, v34, s[40:41]
	v_cndmask_b32_e64 v106, v213, v35, s[56:57]
	v_cndmask_b32_e32 v35, v43, v213, vcc
	v_max3_f32 v34, v98, s86, v99
	v_cndmask_b32_e64 v107, v213, v35, s[58:59]
	v_cndmask_b32_e32 v35, v44, v213, vcc
	v_max3_f32 v34, v34, v100, v101
	v_cndmask_b32_e64 v108, v213, v35, s[60:61]
	v_cndmask_b32_e32 v35, v45, v213, vcc
	v_max3_f32 v34, v34, v102, v103
	v_cndmask_b32_e64 v109, v213, v35, s[62:63]
	v_cndmask_b32_e32 v35, v46, v213, vcc
	v_max3_f32 v34, v34, v104, v105
	v_cndmask_b32_e64 v110, v213, v35, s[64:65]
	v_cndmask_b32_e32 v35, v47, v213, vcc
	v_max3_f32 v34, v34, v106, v107
	v_cndmask_b32_e64 v111, v213, v35, s[66:67]
	v_cndmask_b32_e32 v35, v48, v213, vcc
	v_max3_f32 v34, v34, v108, v109
	v_cndmask_b32_e64 v112, v213, v35, s[68:69]
	v_cndmask_b32_e32 v35, v49, v213, vcc
	v_max3_f32 v34, v34, v110, v111
	v_cndmask_b32_e64 v113, v213, v35, s[70:71]
	v_max3_f32 v34, v34, v112, v113
	s_cmp_gt_i32 s26, 1
	s_cselect_b64 vcc, -1, 0
	v_cndmask_b32_e32 v114, v18, v213, vcc
	v_cndmask_b32_e32 v115, v19, v213, vcc
	v_cndmask_b32_e32 v116, v20, v213, vcc
	v_cndmask_b32_e32 v117, v21, v213, vcc
	v_max3_f32 v18, v34, v114, v115
	v_cndmask_b32_e32 v118, v22, v213, vcc
	v_cndmask_b32_e32 v119, v23, v213, vcc
	v_max3_f32 v18, v18, v116, v117
	v_cndmask_b32_e32 v120, v24, v213, vcc
	v_cndmask_b32_e32 v121, v25, v213, vcc
	v_max3_f32 v18, v18, v118, v119
	v_cndmask_b32_e32 v122, v26, v213, vcc
	v_cndmask_b32_e32 v123, v27, v213, vcc
	v_max3_f32 v18, v18, v120, v121
	v_cndmask_b32_e32 v124, v28, v213, vcc
	v_cndmask_b32_e32 v125, v29, v213, vcc
	v_max3_f32 v18, v18, v122, v123
	v_cndmask_b32_e32 v126, v30, v213, vcc
	v_cndmask_b32_e32 v127, v31, v213, vcc
	s_cmp_gt_i32 s26, 2
	v_max3_f32 v18, v18, v124, v125
	v_cndmask_b32_e32 v128, v32, v213, vcc
	v_cndmask_b32_e32 v129, v33, v213, vcc
	s_cselect_b64 vcc, -1, 0
	v_max3_f32 v18, v18, v126, v127
	v_cndmask_b32_e32 v97, v50, v213, vcc
	v_cndmask_b32_e32 v96, v51, v213, vcc
	v_max3_f32 v18, v18, v128, v129
	v_cndmask_b32_e32 v95, v52, v213, vcc
	v_cndmask_b32_e32 v94, v53, v213, vcc
	v_max3_f32 v18, v18, v97, v96
	v_cndmask_b32_e32 v93, v54, v213, vcc
	v_cndmask_b32_e32 v92, v55, v213, vcc
	v_max3_f32 v18, v18, v95, v94
	v_cndmask_b32_e32 v91, v56, v213, vcc
	v_cndmask_b32_e32 v90, v57, v213, vcc
	v_max3_f32 v18, v18, v93, v92
	v_cndmask_b32_e32 v89, v58, v213, vcc
	v_cndmask_b32_e32 v88, v59, v213, vcc
	v_max3_f32 v18, v18, v91, v90
	v_cndmask_b32_e32 v87, v60, v213, vcc
	v_cndmask_b32_e32 v86, v61, v213, vcc
	v_max3_f32 v18, v18, v89, v88
	v_cndmask_b32_e32 v85, v62, v213, vcc
	v_cndmask_b32_e32 v84, v63, v213, vcc
	s_cmp_gt_i32 s26, 3
	v_max3_f32 v18, v18, v87, v86
	v_cndmask_b32_e32 v83, v64, v213, vcc
	v_cndmask_b32_e32 v82, v65, v213, vcc
	s_cselect_b64 vcc, -1, 0
	v_max3_f32 v18, v18, v85, v84
	v_cndmask_b32_e32 v66, v66, v213, vcc
	v_cndmask_b32_e32 v65, v67, v213, vcc
	v_max3_f32 v18, v18, v83, v82
	v_cndmask_b32_e32 v64, v68, v213, vcc
	v_cndmask_b32_e32 v63, v69, v213, vcc
	v_max3_f32 v18, v18, v66, v65
	v_cndmask_b32_e32 v62, v70, v213, vcc
	v_cndmask_b32_e32 v61, v71, v213, vcc
	v_max3_f32 v18, v18, v64, v63
	v_cndmask_b32_e32 v60, v72, v213, vcc
	v_cndmask_b32_e32 v59, v73, v213, vcc
	v_max3_f32 v18, v18, v62, v61
	v_cndmask_b32_e32 v58, v74, v213, vcc
	v_cndmask_b32_e32 v57, v75, v213, vcc
	v_max3_f32 v18, v18, v60, v59
	v_cndmask_b32_e32 v56, v76, v213, vcc
	v_cndmask_b32_e32 v55, v77, v213, vcc
	v_max3_f32 v18, v18, v58, v57
	v_cndmask_b32_e32 v54, v78, v213, vcc
	v_cndmask_b32_e32 v53, v79, v213, vcc
	v_max3_f32 v18, v18, v56, v55
	v_cndmask_b32_e32 v52, v80, v213, vcc
	v_cndmask_b32_e32 v51, v81, v213, vcc
	v_max3_f32 v18, v18, v54, v53
	v_max3_f32 v18, v18, v52, v51
	v_cndmask_b32_e64 v50, v2, v213, s[40:41]
	v_cndmask_b32_e64 v48, v213, v3, s[42:43]
	v_max3_f32 v2, v18, v50, v48
	v_cndmask_b32_e64 v49, v4, v213, s[44:45]
	v_cndmask_b32_e64 v46, v5, v213, s[46:47]
	v_max3_f32 v2, v2, v49, v46
	v_cndmask_b32_e64 v47, v6, v213, s[48:49]
	v_cndmask_b32_e64 v44, v7, v213, s[50:51]
	v_max3_f32 v2, v2, v47, v44
	v_cndmask_b32_e64 v45, v8, v213, s[52:53]
	v_cndmask_b32_e64 v42, v9, v213, s[54:55]
	v_max3_f32 v2, v2, v45, v42
	v_cndmask_b32_e64 v43, v10, v213, s[56:57]
	v_cndmask_b32_e64 v40, v11, v213, s[58:59]
	v_max3_f32 v2, v2, v43, v40
	v_cndmask_b32_e64 v41, v12, v213, s[60:61]
	v_cndmask_b32_e64 v38, v13, v213, s[62:63]
	v_max3_f32 v2, v2, v41, v38
	v_cndmask_b32_e64 v39, v14, v213, s[64:65]
	v_cndmask_b32_e64 v36, v15, v213, s[66:67]
	v_max3_f32 v2, v2, v39, v36
	v_cndmask_b32_e64 v37, v16, v213, s[68:69]
	v_cndmask_b32_e64 v35, v17, v213, s[70:71]
	v_max3_f32 v2, v2, v37, v35
	ds_bpermute_b32 v3, v171, v2
	s_waitcnt lgkmcnt(0)
	v_max_f32_e32 v3, v3, v3
	v_max_f32_e32 v2, v2, v3
	v_mul_f32_e32 v2, 0x3e38aa3b, v2
	v_max_f32_e32 v3, v228, v228
	v_max_f32_e32 v229, v2, v3
	v_fma_f32 v2, v98, s28, -v229
	v_exp_f32_e32 v76, v2
	v_fma_f32 v2, v99, s28, -v229
	v_exp_f32_e32 v77, v2
	v_fma_f32 v2, v100, s28, -v229
	v_exp_f32_e32 v78, v2
	v_fma_f32 v2, v101, s28, -v229
	v_exp_f32_e32 v79, v2
	v_fma_f32 v2, v102, s28, -v229
	v_exp_f32_e32 v80, v2
	v_fma_f32 v2, v103, s28, -v229
	v_exp_f32_e32 v81, v2
	v_fma_f32 v2, v104, s28, -v229
	v_exp_f32_e32 v98, v2
	v_fma_f32 v2, v105, s28, -v229
	v_exp_f32_e32 v99, v2
	v_fma_f32 v2, v106, s28, -v229
	v_exp_f32_e32 v100, v2
	v_fma_f32 v2, v107, s28, -v229
	v_exp_f32_e32 v101, v2
	v_fma_f32 v2, v108, s28, -v229
	v_exp_f32_e32 v102, v2
	v_fma_f32 v2, v109, s28, -v229
	v_exp_f32_e32 v103, v2
	v_fma_f32 v2, v110, s28, -v229
	v_exp_f32_e32 v104, v2
	v_fma_f32 v2, v111, s28, -v229
	v_exp_f32_e32 v105, v2
	v_fma_f32 v2, v112, s28, -v229
	v_add_u32_e32 v67, s27, v200
	v_exp_f32_e32 v106, v2
	v_fma_f32 v2, v113, s28, -v229
	v_exp_f32_e32 v107, v2
	ds_read_b64_tr_b16 v[2:3], v67 offset:55296
	ds_read_b64_tr_b16 v[4:5], v67 offset:56448
	v_cvt_pk_bf16_f32 v18, v76, v77
	v_cvt_pk_bf16_f32 v19, v78, v79
	v_cvt_pk_bf16_f32 v20, v80, v81
	v_cvt_pk_bf16_f32 v21, v98, v99
	ds_read_b64_tr_b16 v[22:23], v67 offset:55360
	ds_read_b64_tr_b16 v[24:25], v67 offset:56512
	s_waitcnt lgkmcnt(2)
	v_mfma_f32_32x32x16_bf16 v[2:17], v[2:5], v[18:21], 0
	ds_read_b64_tr_b16 v[72:73], v67 offset:57600
	ds_read_b64_tr_b16 v[74:75], v67 offset:58752
	v_cvt_pk_bf16_f32 v68, v100, v101
	v_cvt_pk_bf16_f32 v69, v102, v103
	v_cvt_pk_bf16_f32 v70, v104, v105
	v_cvt_pk_bf16_f32 v71, v106, v107
	v_add_u32_e32 v34, 0xd800, v67
	s_waitcnt lgkmcnt(2)
	v_mfma_f32_32x32x16_bf16 v[18:33], v[22:25], v[18:21], 0
	s_waitcnt lgkmcnt(0)
	v_mfma_f32_32x32x16_bf16 v[2:17], v[72:75], v[68:71], v[2:17]
	ds_read_b64_tr_b16 v[72:73], v67 offset:57664
	ds_read_b64_tr_b16 v[74:75], v67 offset:58816
	s_waitcnt lgkmcnt(0)
	v_mfma_f32_32x32x16_bf16 v[18:33], v[72:75], v[68:71], v[18:33]
	v_add_f32_e32 v68, 0, v76
	v_add_f32_e32 v68, v77, v68
	v_add_f32_e32 v68, v78, v68
	v_add_f32_e32 v68, v79, v68
	v_add_f32_e32 v68, v80, v68
	v_add_f32_e32 v68, v81, v68
	v_add_f32_e32 v68, v98, v68
	v_add_f32_e32 v68, v99, v68
	v_add_f32_e32 v68, v100, v68
	v_add_f32_e32 v68, v101, v68
	v_add_f32_e32 v68, v102, v68
	v_add_f32_e32 v68, v103, v68
	v_add_f32_e32 v68, v104, v68
	v_add_f32_e32 v68, v105, v68
	v_add_f32_e32 v68, v106, v68
	v_add_f32_e32 v76, v107, v68
	v_fma_f32 v68, v114, s28, -v229
	v_exp_f32_e32 v77, v68
	v_fma_f32 v68, v115, s28, -v229
	v_exp_f32_e32 v78, v68
	v_fma_f32 v68, v116, s28, -v229
	v_exp_f32_e32 v79, v68
	v_fma_f32 v68, v117, s28, -v229
	v_exp_f32_e32 v80, v68
	v_fma_f32 v68, v118, s28, -v229
	v_exp_f32_e32 v81, v68
	v_fma_f32 v68, v119, s28, -v229
	v_exp_f32_e32 v98, v68
	v_fma_f32 v68, v120, s28, -v229
	v_exp_f32_e32 v99, v68
	v_fma_f32 v68, v121, s28, -v229
	v_exp_f32_e32 v100, v68
	v_fma_f32 v68, v122, s28, -v229
	v_exp_f32_e32 v101, v68
	v_fma_f32 v68, v123, s28, -v229
	v_exp_f32_e32 v102, v68
	v_fma_f32 v68, v124, s28, -v229
	v_exp_f32_e32 v103, v68
	v_fma_f32 v68, v125, s28, -v229
	v_exp_f32_e32 v104, v68
	v_fma_f32 v68, v126, s28, -v229
	ds_read_b64_tr_b16 v[72:73], v67 offset:59904
	ds_read_b64_tr_b16 v[74:75], v67 offset:61056
	v_exp_f32_e32 v105, v68
	v_fma_f32 v68, v127, s28, -v229
	v_exp_f32_e32 v106, v68
	v_fma_f32 v68, v128, s28, -v229
	v_exp_f32_e32 v107, v68
	v_fma_f32 v68, v129, s28, -v229
	v_exp_f32_e32 v108, v68
	v_cvt_pk_bf16_f32 v68, v77, v78
	v_cvt_pk_bf16_f32 v69, v79, v80
	v_cvt_pk_bf16_f32 v70, v81, v98
	v_cvt_pk_bf16_f32 v71, v99, v100
	s_waitcnt lgkmcnt(0)
	s_nop 0
	v_mfma_f32_32x32x16_bf16 v[2:17], v[72:75], v[68:71], v[2:17]
	ds_read_b64_tr_b16 v[72:73], v67 offset:59968
	ds_read_b64_tr_b16 v[74:75], v67 offset:61120
	s_waitcnt lgkmcnt(0)
	v_mfma_f32_32x32x16_bf16 v[18:33], v[72:75], v[68:71], v[18:33]
	ds_read_b64_tr_b16 v[72:73], v67 offset:62208
	ds_read_b64_tr_b16 v[74:75], v67 offset:63360
	v_cvt_pk_bf16_f32 v68, v101, v102
	v_cvt_pk_bf16_f32 v69, v103, v104
	v_cvt_pk_bf16_f32 v70, v105, v106
	v_cvt_pk_bf16_f32 v71, v107, v108
	s_waitcnt lgkmcnt(0)
	s_nop 0
	v_mfma_f32_32x32x16_bf16 v[2:17], v[72:75], v[68:71], v[2:17]
	ds_read_b64_tr_b16 v[72:73], v67 offset:62272
	ds_read_b64_tr_b16 v[74:75], v67 offset:63424
	s_waitcnt lgkmcnt(0)
	v_mfma_f32_32x32x16_bf16 v[18:33], v[72:75], v[68:71], v[18:33]
	v_add_f32_e32 v68, v77, v76
	v_add_f32_e32 v68, v78, v68
	v_add_f32_e32 v68, v79, v68
	v_add_f32_e32 v68, v80, v68
	v_add_f32_e32 v68, v81, v68
	v_add_f32_e32 v68, v98, v68
	v_add_f32_e32 v68, v99, v68
	v_add_f32_e32 v68, v100, v68
	v_add_f32_e32 v68, v101, v68
	v_add_f32_e32 v68, v102, v68
	v_add_f32_e32 v68, v103, v68
	v_add_f32_e32 v68, v104, v68
	v_add_f32_e32 v68, v105, v68
	v_add_f32_e32 v68, v106, v68
	v_add_f32_e32 v68, v107, v68
	v_add_f32_e32 v76, v108, v68
	v_fma_f32 v68, v97, s28, -v229
	v_exp_f32_e32 v77, v68
	v_fma_f32 v68, v96, s28, -v229
	v_exp_f32_e32 v78, v68
	v_fma_f32 v68, v95, s28, -v229
	v_exp_f32_e32 v79, v68
	v_fma_f32 v68, v94, s28, -v229
	v_exp_f32_e32 v80, v68
	v_fma_f32 v68, v93, s28, -v229
	v_exp_f32_e32 v81, v68
	v_fma_f32 v68, v92, s28, -v229
	v_exp_f32_e32 v92, v68
	v_fma_f32 v68, v91, s28, -v229
	v_exp_f32_e32 v91, v68
	v_fma_f32 v68, v90, s28, -v229
	v_exp_f32_e32 v90, v68
	v_fma_f32 v68, v89, s28, -v229
	v_exp_f32_e32 v89, v68
	v_fma_f32 v68, v88, s28, -v229
	v_exp_f32_e32 v88, v68
	v_fma_f32 v68, v87, s28, -v229
	v_exp_f32_e32 v87, v68
	v_fma_f32 v68, v86, s28, -v229
	v_exp_f32_e32 v86, v68
	v_fma_f32 v68, v85, s28, -v229
	ds_read_b64_tr_b16 v[72:73], v67 offset:64512
	ds_read_b64_tr_b16 v[74:75], v34 offset:10368
	v_exp_f32_e32 v85, v68
	v_fma_f32 v68, v84, s28, -v229
	v_exp_f32_e32 v84, v68
	v_fma_f32 v68, v83, s28, -v229
	v_exp_f32_e32 v83, v68
	v_fma_f32 v68, v82, s28, -v229
	v_exp_f32_e32 v82, v68
	v_cvt_pk_bf16_f32 v68, v77, v78
	v_cvt_pk_bf16_f32 v69, v79, v80
	v_cvt_pk_bf16_f32 v70, v81, v92
	v_cvt_pk_bf16_f32 v71, v91, v90
	s_waitcnt lgkmcnt(0)
	s_nop 0
	v_mfma_f32_32x32x16_bf16 v[2:17], v[72:75], v[68:71], v[2:17]
	ds_read_b64_tr_b16 v[72:73], v67 offset:64576
	ds_read_b64_tr_b16 v[74:75], v34 offset:10432
	v_add_f32_e32 v67, v77, v76
	v_add_f32_e32 v67, v78, v67
	v_add_f32_e32 v67, v79, v67
	v_add_f32_e32 v67, v80, v67
	v_add_f32_e32 v67, v81, v67
	v_add_f32_e32 v67, v92, v67
	s_waitcnt lgkmcnt(0)
	v_mfma_f32_32x32x16_bf16 v[18:33], v[72:75], v[68:71], v[18:33]
	ds_read_b64_tr_b16 v[72:73], v34 offset:11520
	ds_read_b64_tr_b16 v[74:75], v34 offset:12672
	v_cvt_pk_bf16_f32 v68, v89, v88
	v_cvt_pk_bf16_f32 v69, v87, v86
	v_cvt_pk_bf16_f32 v70, v85, v84
	v_cvt_pk_bf16_f32 v71, v83, v82
	v_add_f32_e32 v67, v91, v67
	v_add_f32_e32 v67, v90, v67
	s_waitcnt lgkmcnt(0)
	v_mfma_f32_32x32x16_bf16 v[2:17], v[72:75], v[68:71], v[2:17]
	ds_read_b64_tr_b16 v[72:73], v34 offset:11584
	ds_read_b64_tr_b16 v[74:75], v34 offset:12736
	v_add_f32_e32 v67, v89, v67
	v_add_f32_e32 v67, v88, v67
	v_add_f32_e32 v67, v87, v67
	v_add_f32_e32 v67, v86, v67
	v_add_f32_e32 v67, v85, v67
	v_add_f32_e32 v67, v84, v67
	s_waitcnt lgkmcnt(0)
	v_mfma_f32_32x32x16_bf16 v[18:33], v[72:75], v[68:71], v[18:33]
	v_add_f32_e32 v67, v83, v67
	v_add_f32_e32 v67, v82, v67
	v_fma_f32 v66, v66, s28, -v229
	v_fma_f32 v65, v65, s28, -v229
	v_fma_f32 v64, v64, s28, -v229
	v_fma_f32 v63, v63, s28, -v229
	v_fma_f32 v62, v62, s28, -v229
	v_fma_f32 v61, v61, s28, -v229
	v_fma_f32 v60, v60, s28, -v229
	v_fma_f32 v59, v59, s28, -v229
	v_fma_f32 v58, v58, s28, -v229
	v_fma_f32 v57, v57, s28, -v229
	v_fma_f32 v56, v56, s28, -v229
	v_exp_f32_e32 v66, v66
	v_exp_f32_e32 v65, v65
	v_exp_f32_e32 v64, v64
	v_exp_f32_e32 v63, v63
	v_exp_f32_e32 v62, v62
	v_exp_f32_e32 v61, v61
	v_exp_f32_e32 v60, v60
	v_exp_f32_e32 v68, v59
	v_exp_f32_e32 v69, v58
	v_exp_f32_e32 v70, v57
	v_exp_f32_e32 v71, v56
	ds_read_b64_tr_b16 v[56:57], v34 offset:13824
	ds_read_b64_tr_b16 v[58:59], v34 offset:14976
	v_fma_f32 v55, v55, s28, -v229
	v_fma_f32 v54, v54, s28, -v229
	v_fma_f32 v53, v53, s28, -v229
	v_fma_f32 v52, v52, s28, -v229
	v_exp_f32_e32 v72, v55
	v_exp_f32_e32 v73, v54
	v_exp_f32_e32 v74, v53
	v_exp_f32_e32 v75, v52
	v_cvt_pk_bf16_f32 v52, v66, v65
	v_cvt_pk_bf16_f32 v53, v64, v63
	v_cvt_pk_bf16_f32 v54, v62, v61
	v_cvt_pk_bf16_f32 v55, v60, v68
	v_fma_f32 v51, v51, s28, -v229
	v_exp_f32_e32 v51, v51
	s_waitcnt lgkmcnt(0)
	v_mfma_f32_32x32x16_bf16 v[2:17], v[56:59], v[52:55], v[2:17]
	ds_read_b64_tr_b16 v[56:57], v34 offset:13888
	ds_read_b64_tr_b16 v[58:59], v34 offset:15040
	s_waitcnt lgkmcnt(0)
	v_mfma_f32_32x32x16_bf16 v[18:33], v[56:59], v[52:55], v[18:33]
	ds_read_b64_tr_b16 v[56:57], v34 offset:16128
	ds_read_b64_tr_b16 v[58:59], v34 offset:17280
	v_cvt_pk_bf16_f32 v52, v69, v70
	v_cvt_pk_bf16_f32 v53, v71, v72
	v_cvt_pk_bf16_f32 v54, v73, v74
	v_cvt_pk_bf16_f32 v55, v75, v51
	s_waitcnt lgkmcnt(0)
	s_nop 0
	v_mfma_f32_32x32x16_bf16 v[2:17], v[56:59], v[52:55], v[2:17]
	ds_read_b64_tr_b16 v[56:57], v34 offset:16192
	ds_read_b64_tr_b16 v[58:59], v34 offset:17344
	s_waitcnt lgkmcnt(0)
	v_mfma_f32_32x32x16_bf16 v[18:33], v[56:59], v[52:55], v[18:33]
	v_add_f32_e32 v52, v66, v67
	v_add_f32_e32 v52, v65, v52
	v_add_f32_e32 v52, v64, v52
	v_add_f32_e32 v52, v63, v52
	v_add_f32_e32 v52, v62, v52
	v_add_f32_e32 v52, v61, v52
	v_add_f32_e32 v52, v60, v52
	v_add_f32_e32 v52, v68, v52
	v_add_f32_e32 v52, v69, v52
	v_add_f32_e32 v52, v70, v52
	v_add_f32_e32 v52, v71, v52
	v_add_f32_e32 v52, v72, v52
	v_add_f32_e32 v52, v73, v52
	v_add_f32_e32 v52, v74, v52
	v_add_f32_e32 v52, v75, v52
	v_add_f32_e32 v51, v51, v52
	v_fma_f32 v42, v42, s28, -v229
	v_fma_f32 v40, v40, s28, -v229
	v_fma_f32 v50, v50, s28, -v229
	v_fma_f32 v48, v48, s28, -v229
	v_fma_f32 v49, v49, s28, -v229
	v_fma_f32 v46, v46, s28, -v229
	v_fma_f32 v47, v47, s28, -v229
	v_fma_f32 v44, v44, s28, -v229
	v_fma_f32 v45, v45, s28, -v229
	v_exp_f32_e32 v52, v42
	v_fma_f32 v42, v43, s28, -v229
	v_exp_f32_e32 v54, v40
	v_fma_f32 v40, v41, s28, -v229
	v_exp_f32_e32 v50, v50
	v_exp_f32_e32 v48, v48
	v_exp_f32_e32 v49, v49
	v_exp_f32_e32 v46, v46
	v_exp_f32_e32 v47, v47
	v_exp_f32_e32 v44, v44
	v_exp_f32_e32 v45, v45
	v_exp_f32_e32 v53, v42
	v_exp_f32_e32 v55, v40
	ds_read_b64_tr_b16 v[40:41], v34 offset:18432
	ds_read_b64_tr_b16 v[42:43], v34 offset:19584
	v_fma_f32 v38, v38, s28, -v229
	v_fma_f32 v36, v36, s28, -v229
	v_exp_f32_e32 v56, v38
	v_fma_f32 v38, v39, s28, -v229
	v_exp_f32_e32 v58, v36
	v_fma_f32 v36, v37, s28, -v229
	v_exp_f32_e32 v57, v38
	v_exp_f32_e32 v59, v36
	v_cvt_pk_bf16_f32 v36, v50, v48
	v_cvt_pk_bf16_f32 v37, v49, v46
	v_cvt_pk_bf16_f32 v38, v47, v44
	v_cvt_pk_bf16_f32 v39, v45, v52
	v_fma_f32 v35, v35, s28, -v229
	v_exp_f32_e32 v35, v35
	s_waitcnt lgkmcnt(0)
	v_mfma_f32_32x32x16_bf16 v[2:17], v[40:43], v[36:39], v[2:17]
	ds_read_b64_tr_b16 v[40:41], v34 offset:18496
	ds_read_b64_tr_b16 v[42:43], v34 offset:19648
	s_waitcnt lgkmcnt(0)
	v_mfma_f32_32x32x16_bf16 v[18:33], v[40:43], v[36:39], v[18:33]
	ds_read_b64_tr_b16 v[40:41], v34 offset:20736
	ds_read_b64_tr_b16 v[42:43], v34 offset:21888
	v_cvt_pk_bf16_f32 v36, v53, v54
	v_cvt_pk_bf16_f32 v37, v55, v56
	v_cvt_pk_bf16_f32 v38, v57, v58
	v_cvt_pk_bf16_f32 v39, v59, v35
	s_waitcnt lgkmcnt(0)
	s_nop 0
	v_mfma_f32_32x32x16_bf16 v[2:17], v[40:43], v[36:39], v[2:17]
	ds_read_b64_tr_b16 v[40:41], v34 offset:20800
	ds_read_b64_tr_b16 v[42:43], v34 offset:21952
	v_add_f32_e32 v34, v50, v51
	v_add_f32_e32 v34, v48, v34
	v_add_f32_e32 v34, v49, v34
	v_add_f32_e32 v34, v46, v34
	v_add_f32_e32 v34, v47, v34
	v_add_f32_e32 v34, v44, v34
	v_add_f32_e32 v34, v45, v34
	v_add_f32_e32 v34, v52, v34
	s_waitcnt lgkmcnt(0)
	v_mfma_f32_32x32x16_bf16 v[18:33], v[40:43], v[36:39], v[18:33]
	v_add_f32_e32 v34, v53, v34
	v_add_f32_e32 v34, v54, v34
	v_add_f32_e32 v34, v55, v34
	v_add_f32_e32 v34, v56, v34
	v_add_f32_e32 v34, v57, v34
	v_add_f32_e32 v34, v58, v34
	v_add_f32_e32 v34, v59, v34
	v_add_f32_e32 v34, v35, v34

.LBB0_1066:
	s_ashr_i32 s23, s22, 31
	s_lshl_b64 s[26:27], s[22:23], 19
	s_add_u32 s30, s16, s26
	s_addc_u32 s31, s52, s27
	s_and_b64 s[26:27], s[36:37], exec
	s_cselect_b32 s21, s31, s45
	s_cselect_b32 s23, s30, s44
	s_ashr_i32 s19, s18, 31
	s_lshl_b64 s[26:27], s[18:19], 19
	s_add_u32 s40, s53, s26
	s_addc_u32 s41, s54, s27
	s_and_b64 s[26:27], s[36:37], exec
	s_cselect_b32 s19, s41, s47
	s_cselect_b32 s26, s40, s46
	s_add_u32 s44, s44, 0x40080
	s_addc_u32 s45, s45, 0
	s_add_u32 s27, s46, 0x100
	v_mov_b32_e32 v2, 0
	s_addc_u32 s29, s47, 0
	s_mov_b32 s34, -2
	v_mov_b32_e32 v3, v2
	v_mov_b32_e32 v4, v2
	v_mov_b32_e32 v5, v2
	v_mov_b32_e32 v6, v2
	v_mov_b32_e32 v7, v2
	v_mov_b32_e32 v8, v2
	v_mov_b32_e32 v9, v2
	v_mov_b32_e32 v18, v2
	v_mov_b32_e32 v19, v2
	v_mov_b32_e32 v20, v2
	v_mov_b32_e32 v21, v2
	v_mov_b32_e32 v22, v2
	v_mov_b32_e32 v23, v2
	v_mov_b32_e32 v24, v2
	v_mov_b32_e32 v25, v2
	v_mov_b32_e32 v34, v2
	v_mov_b32_e32 v35, v2
	v_mov_b32_e32 v36, v2
	v_mov_b32_e32 v37, v2
	v_mov_b32_e32 v38, v2
	v_mov_b32_e32 v39, v2
	v_mov_b32_e32 v40, v2
	v_mov_b32_e32 v41, v2
	v_mov_b32_e32 v50, v2
	v_mov_b32_e32 v51, v2
	v_mov_b32_e32 v52, v2
	v_mov_b32_e32 v53, v2
	v_mov_b32_e32 v54, v2
	v_mov_b32_e32 v55, v2
	v_mov_b32_e32 v56, v2
	v_mov_b32_e32 v57, v2
	v_mov_b32_e32 v10, v2
	v_mov_b32_e32 v11, v2
	v_mov_b32_e32 v12, v2
	v_mov_b32_e32 v13, v2
	v_mov_b32_e32 v14, v2
	v_mov_b32_e32 v15, v2
	v_mov_b32_e32 v16, v2
	v_mov_b32_e32 v17, v2
	v_mov_b32_e32 v26, v2
	v_mov_b32_e32 v27, v2
	v_mov_b32_e32 v28, v2
	v_mov_b32_e32 v29, v2
	v_mov_b32_e32 v30, v2
	v_mov_b32_e32 v31, v2
	v_mov_b32_e32 v32, v2
	v_mov_b32_e32 v33, v2
	v_mov_b32_e32 v42, v2
	v_mov_b32_e32 v43, v2
	v_mov_b32_e32 v44, v2
	v_mov_b32_e32 v45, v2
	v_mov_b32_e32 v46, v2
	v_mov_b32_e32 v47, v2
	v_mov_b32_e32 v48, v2
	v_mov_b32_e32 v49, v2
	v_mov_b32_e32 v58, v2
	v_mov_b32_e32 v59, v2
	v_mov_b32_e32 v60, v2
	v_mov_b32_e32 v61, v2
	v_mov_b32_e32 v62, v2
	v_mov_b32_e32 v63, v2
	v_mov_b32_e32 v64, v2
	v_mov_b32_e32 v65, v2
	v_mov_b32_e32 v66, v2
	v_mov_b32_e32 v67, v2
	v_mov_b32_e32 v68, v2
	v_mov_b32_e32 v69, v2
	v_mov_b32_e32 v70, v2
	v_mov_b32_e32 v71, v2
	v_mov_b32_e32 v72, v2
	v_mov_b32_e32 v73, v2
	v_mov_b32_e32 v82, v2
	v_mov_b32_e32 v83, v2
	v_mov_b32_e32 v84, v2
	v_mov_b32_e32 v85, v2
	v_mov_b32_e32 v86, v2
	v_mov_b32_e32 v87, v2
	v_mov_b32_e32 v88, v2
	v_mov_b32_e32 v89, v2
	v_mov_b32_e32 v98, v2
	v_mov_b32_e32 v99, v2
	v_mov_b32_e32 v100, v2
	v_mov_b32_e32 v101, v2
	v_mov_b32_e32 v102, v2
	v_mov_b32_e32 v103, v2
	v_mov_b32_e32 v104, v2
	v_mov_b32_e32 v105, v2
	v_mov_b32_e32 v114, v2
	v_mov_b32_e32 v115, v2
	v_mov_b32_e32 v116, v2
	v_mov_b32_e32 v117, v2
	v_mov_b32_e32 v118, v2
	v_mov_b32_e32 v119, v2
	v_mov_b32_e32 v120, v2
	v_mov_b32_e32 v121, v2
	v_mov_b32_e32 v74, v2
	v_mov_b32_e32 v75, v2
	v_mov_b32_e32 v76, v2
	v_mov_b32_e32 v77, v2
	v_mov_b32_e32 v78, v2
	v_mov_b32_e32 v79, v2
	v_mov_b32_e32 v80, v2
	v_mov_b32_e32 v81, v2
	v_mov_b32_e32 v90, v2
	v_mov_b32_e32 v91, v2
	v_mov_b32_e32 v92, v2
	v_mov_b32_e32 v93, v2
	v_mov_b32_e32 v94, v2
	v_mov_b32_e32 v95, v2
	v_mov_b32_e32 v96, v2
	v_mov_b32_e32 v97, v2
	v_mov_b32_e32 v106, v2
	v_mov_b32_e32 v107, v2
	v_mov_b32_e32 v108, v2
	v_mov_b32_e32 v109, v2
	v_mov_b32_e32 v110, v2
	v_mov_b32_e32 v111, v2
	v_mov_b32_e32 v112, v2
	v_mov_b32_e32 v113, v2
	v_mov_b32_e32 v122, v2
	v_mov_b32_e32 v123, v2
	v_mov_b32_e32 v124, v2
	v_mov_b32_e32 v125, v2
	v_mov_b32_e32 v126, v2
	v_mov_b32_e32 v127, v2
	v_mov_b32_e32 v128, v2
	v_mov_b32_e32 v129, v2
	s_cmp_eq_u32 s20, 0
	s_cbranch_scc1 .Ltb_hg_skip
	s_cmp_eq_u32 s4, 0
	s_cbranch_scc1 .Ltb_hg_skip
	s_barrier
.Ltb_hg_skip:
.LBB0_1067:
	s_add_u32 s39, s44, 0xfffc0080
	s_addc_u32 s43, s45, -1
	s_add_i32 s50, 0, 0x10000
	s_cmp_eq_u32 s34, 12
	s_cselect_b32 s49, s21, s43
	s_cselect_b32 s48, s23, s39
	s_cselect_b32 s47, s19, s29
	s_cselect_b32 s46, s26, s27
	s_add_i32 s39, 0, 0x14000
	v_add_u32_e32 v142, s50, v222
	v_add_u32_e32 v166, s39, v222
	ds_read_b128 v[130:133], v142
	ds_read_b128 v[134:137], v142 offset:1024
	ds_read_b128 v[138:141], v142 offset:2048
	ds_read_b128 v[142:145], v142 offset:3072
	s_waitcnt lgkmcnt(0)
	ds_read_b128 v[174:177], v166
	ds_read_b128 v[178:181], v166 offset:1024
	ds_read_b128 v[182:185], v166 offset:2048
	ds_read_b128 v[186:189], v166 offset:3072
	v_lshl_add_u64 v[244:245], s[44:45], 0, v[162:163]
	s_add_i32 m0, s55, 0xc000
	ds_read_b128 v[190:193], v157
	ds_read_b128 v[194:197], v157 offset:1024
	ds_read_b128 v[198:201], v157 offset:2048
	ds_read_b128 v[202:205], v157 offset:3072
	ds_read_b128 v[228:231], v157 offset:4096
	ds_read_b128 v[232:235], v157 offset:5120
	ds_read_b128 v[236:239], v157 offset:6144
	ds_read_b128 v[240:243], v157 offset:7168
	global_load_lds_dwordx4 v[244:245], off
	v_lshl_add_u64 v[244:245], s[44:45], 0, v[164:165]
	s_add_i32 m0, s55, 0xe000
	s_nop 0
	global_load_lds_dwordx4 v[244:245], off
	s_waitcnt vmcnt(8)
	s_waitcnt lgkmcnt(0)
	s_barrier
	s_setprio 1
	s_waitcnt lgkmcnt(0)
	v_mfma_f32_16x16x32_bf16 v[126:129], v[130:133], v[190:193], v[126:129]
	v_mfma_f32_16x16x32_bf16 v[122:125], v[138:141], v[190:193], v[122:125]
	v_mfma_f32_16x16x32_bf16 v[110:113], v[130:133], v[198:201], v[110:113]
	v_mfma_f32_16x16x32_bf16 v[106:109], v[138:141], v[198:201], v[106:109]
	v_mfma_f32_16x16x32_bf16 v[94:97], v[130:133], v[228:231], v[94:97]
	v_mfma_f32_16x16x32_bf16 v[90:93], v[138:141], v[228:231], v[90:93]
	v_mfma_f32_16x16x32_bf16 v[78:81], v[130:133], v[236:239], v[78:81]
	v_mfma_f32_16x16x32_bf16 v[74:77], v[138:141], v[236:239], v[74:77]
	v_mfma_f32_16x16x32_bf16 v[126:129], v[134:137], v[194:197], v[126:129]
	v_mfma_f32_16x16x32_bf16 v[122:125], v[142:145], v[194:197], v[122:125]
	v_mfma_f32_16x16x32_bf16 v[110:113], v[134:137], v[202:205], v[110:113]
	v_mfma_f32_16x16x32_bf16 v[106:109], v[142:145], v[202:205], v[106:109]
	v_mfma_f32_16x16x32_bf16 v[94:97], v[134:137], v[232:235], v[94:97]
	v_mfma_f32_16x16x32_bf16 v[90:93], v[142:145], v[232:235], v[90:93]
	v_mfma_f32_16x16x32_bf16 v[78:81], v[134:137], v[240:243], v[78:81]
	v_mfma_f32_16x16x32_bf16 v[74:77], v[142:145], v[240:243], v[74:77]
	s_setprio 0
	s_setprio 1
	v_mfma_f32_16x16x32_bf16 v[118:121], v[174:177], v[190:193], v[118:121]
	v_mfma_f32_16x16x32_bf16 v[114:117], v[182:185], v[190:193], v[114:117]
	v_mfma_f32_16x16x32_bf16 v[102:105], v[174:177], v[198:201], v[102:105]
	v_mfma_f32_16x16x32_bf16 v[98:101], v[182:185], v[198:201], v[98:101]
	v_mfma_f32_16x16x32_bf16 v[86:89], v[174:177], v[228:231], v[86:89]
	v_mfma_f32_16x16x32_bf16 v[82:85], v[182:185], v[228:231], v[82:85]
	v_mfma_f32_16x16x32_bf16 v[70:73], v[174:177], v[236:239], v[70:73]
	v_mfma_f32_16x16x32_bf16 v[66:69], v[182:185], v[236:239], v[66:69]
	v_mfma_f32_16x16x32_bf16 v[118:121], v[178:181], v[194:197], v[118:121]
	v_mfma_f32_16x16x32_bf16 v[114:117], v[186:189], v[194:197], v[114:117]
	v_mfma_f32_16x16x32_bf16 v[102:105], v[178:181], v[202:205], v[102:105]
	v_mfma_f32_16x16x32_bf16 v[98:101], v[186:189], v[202:205], v[98:101]
	v_mfma_f32_16x16x32_bf16 v[86:89], v[178:181], v[232:235], v[86:89]
	v_mfma_f32_16x16x32_bf16 v[82:85], v[186:189], v[232:235], v[82:85]
	v_mfma_f32_16x16x32_bf16 v[70:73], v[178:181], v[240:243], v[70:73]
	v_mfma_f32_16x16x32_bf16 v[66:69], v[186:189], v[240:243], v[66:69]
	s_setprio 0
	s_barrier
	s_add_i32 s43, s50, s13
	v_lshl_add_u64 v[244:245], s[46:47], 0, v[0:1]
	s_mov_b32 m0, s43
	ds_read_b128 v[190:193], v157 offset:16384
	ds_read_b128 v[194:197], v157 offset:17408
	ds_read_b128 v[198:201], v157 offset:18432
	ds_read_b128 v[202:205], v157 offset:19456
	ds_read_b128 v[228:231], v157 offset:20480
	ds_read_b128 v[232:235], v157 offset:21504
	ds_read_b128 v[236:239], v157 offset:22528
	ds_read_b128 v[240:243], v157 offset:23552
	global_load_lds_dwordx4 v[244:245], off
	s_add_i32 m0, s43, 0x2000
	s_add_u32 s50, s46, 0x40000
	v_lshl_add_u64 v[246:247], s[46:47], 0, v[154:155]
	s_addc_u32 s51, s47, 0
	s_add_i32 s39, s39, s13
	global_load_lds_dwordx4 v[246:247], off
	v_lshl_add_u64 v[248:249], s[50:51], 0, v[0:1]
	s_mov_b32 m0, s39
	v_lshl_add_u64 v[250:251], s[48:49], 0, v[152:153]
	global_load_lds_dwordx4 v[248:249], off
	v_lshl_add_u64 v[248:249], s[50:51], 0, v[154:155]
	s_add_i32 m0, s39, 0x2000
	s_nop 0
	global_load_lds_dwordx4 v[248:249], off
	v_lshl_add_u64 v[248:249], s[48:49], 0, v[150:151]
	s_mov_b32 m0, s55
	s_nop 0
	global_load_lds_dwordx4 v[248:249], off
	s_mov_b32 m0, s56
	s_nop 0
	global_load_lds_dwordx4 v[250:251], off
	s_waitcnt vmcnt(8)
	s_waitcnt lgkmcnt(0)
	s_barrier
	s_setprio 1
	s_waitcnt lgkmcnt(0)
	v_mfma_f32_16x16x32_bf16 v[62:65], v[130:133], v[190:193], v[62:65]
	v_mfma_f32_16x16x32_bf16 v[58:61], v[138:141], v[190:193], v[58:61]
	v_mfma_f32_16x16x32_bf16 v[46:49], v[130:133], v[198:201], v[46:49]
	v_mfma_f32_16x16x32_bf16 v[42:45], v[138:141], v[198:201], v[42:45]
	v_mfma_f32_16x16x32_bf16 v[30:33], v[130:133], v[228:231], v[30:33]
	v_mfma_f32_16x16x32_bf16 v[26:29], v[138:141], v[228:231], v[26:29]
	v_mfma_f32_16x16x32_bf16 v[14:17], v[130:133], v[236:239], v[14:17]
	v_mfma_f32_16x16x32_bf16 v[10:13], v[138:141], v[236:239], v[10:13]
	v_mfma_f32_16x16x32_bf16 v[62:65], v[134:137], v[194:197], v[62:65]
	v_mfma_f32_16x16x32_bf16 v[58:61], v[142:145], v[194:197], v[58:61]
	v_mfma_f32_16x16x32_bf16 v[46:49], v[134:137], v[202:205], v[46:49]
	v_mfma_f32_16x16x32_bf16 v[42:45], v[142:145], v[202:205], v[42:45]
	v_mfma_f32_16x16x32_bf16 v[30:33], v[134:137], v[232:235], v[30:33]
	v_mfma_f32_16x16x32_bf16 v[26:29], v[142:145], v[232:235], v[26:29]
	v_mfma_f32_16x16x32_bf16 v[14:17], v[134:137], v[240:243], v[14:17]
	v_mfma_f32_16x16x32_bf16 v[10:13], v[142:145], v[240:243], v[10:13]
	s_setprio 0
	s_setprio 1
	v_mfma_f32_16x16x32_bf16 v[54:57], v[174:177], v[190:193], v[54:57]
	v_mfma_f32_16x16x32_bf16 v[50:53], v[182:185], v[190:193], v[50:53]
	v_mfma_f32_16x16x32_bf16 v[38:41], v[174:177], v[198:201], v[38:41]
	v_mfma_f32_16x16x32_bf16 v[34:37], v[182:185], v[198:201], v[34:37]
	v_mfma_f32_16x16x32_bf16 v[22:25], v[174:177], v[228:231], v[22:25]
	v_mfma_f32_16x16x32_bf16 v[18:21], v[182:185], v[228:231], v[18:21]
	v_mfma_f32_16x16x32_bf16 v[6:9], v[174:177], v[236:239], v[6:9]
	v_mfma_f32_16x16x32_bf16 v[2:5], v[182:185], v[236:239], v[2:5]
	v_mfma_f32_16x16x32_bf16 v[54:57], v[178:181], v[194:197], v[54:57]
	v_mfma_f32_16x16x32_bf16 v[50:53], v[186:189], v[194:197], v[50:53]
	v_mfma_f32_16x16x32_bf16 v[38:41], v[178:181], v[202:205], v[38:41]
	v_mfma_f32_16x16x32_bf16 v[34:37], v[186:189], v[202:205], v[34:37]
	v_mfma_f32_16x16x32_bf16 v[22:25], v[178:181], v[232:235], v[22:25]
	v_mfma_f32_16x16x32_bf16 v[18:21], v[186:189], v[232:235], v[18:21]
	v_mfma_f32_16x16x32_bf16 v[6:9], v[178:181], v[240:243], v[6:9]
	v_mfma_f32_16x16x32_bf16 v[2:5], v[186:189], v[240:243], v[2:5]
	s_setprio 0
	s_barrier
	s_add_i32 s39, 0, 0x18000
	s_add_i32 s43, 0, 0x1c000
	v_add_u32_e32 v142, s39, v222
	v_add_u32_e32 v166, s43, v222
	ds_read_b128 v[130:133], v142
	ds_read_b128 v[134:137], v142 offset:1024
	ds_read_b128 v[138:141], v142 offset:2048
	ds_read_b128 v[142:145], v142 offset:3072
	ds_read_b128 v[174:177], v166
	ds_read_b128 v[178:181], v166 offset:1024
	ds_read_b128 v[182:185], v166 offset:2048
	ds_read_b128 v[186:189], v166 offset:3072
	s_add_u32 s48, s48, 0x40000
	s_addc_u32 s49, s49, 0
	s_mov_b32 m0, s57
	v_lshl_add_u64 v[166:167], s[48:49], 0, v[150:151]
	ds_read_b128 v[190:193], v157 offset:32768
	ds_read_b128 v[194:197], v157 offset:33792
	ds_read_b128 v[198:201], v157 offset:34816
	ds_read_b128 v[202:205], v157 offset:35840
	ds_read_b128 v[228:231], v157 offset:36864
	ds_read_b128 v[232:235], v157 offset:37888
	ds_read_b128 v[236:239], v157 offset:38912
	ds_read_b128 v[240:243], v157 offset:39936
	global_load_lds_dwordx4 v[166:167], off
	v_lshl_add_u64 v[166:167], s[48:49], 0, v[152:153]
	s_mov_b32 m0, s58
	s_nop 0
	global_load_lds_dwordx4 v[166:167], off
	s_waitcnt vmcnt(8)
	s_waitcnt lgkmcnt(0)
	s_barrier
	s_setprio 1
	s_waitcnt lgkmcnt(0)
	v_mfma_f32_16x16x32_bf16 v[126:129], v[130:133], v[190:193], v[126:129]
	v_mfma_f32_16x16x32_bf16 v[122:125], v[138:141], v[190:193], v[122:125]
	v_mfma_f32_16x16x32_bf16 v[110:113], v[130:133], v[198:201], v[110:113]
	v_mfma_f32_16x16x32_bf16 v[106:109], v[138:141], v[198:201], v[106:109]
	v_mfma_f32_16x16x32_bf16 v[94:97], v[130:133], v[228:231], v[94:97]
	v_mfma_f32_16x16x32_bf16 v[90:93], v[138:141], v[228:231], v[90:93]
	v_mfma_f32_16x16x32_bf16 v[78:81], v[130:133], v[236:239], v[78:81]
	v_mfma_f32_16x16x32_bf16 v[74:77], v[138:141], v[236:239], v[74:77]
	v_mfma_f32_16x16x32_bf16 v[126:129], v[134:137], v[194:197], v[126:129]
	v_mfma_f32_16x16x32_bf16 v[122:125], v[142:145], v[194:197], v[122:125]
	v_mfma_f32_16x16x32_bf16 v[110:113], v[134:137], v[202:205], v[110:113]
	v_mfma_f32_16x16x32_bf16 v[106:109], v[142:145], v[202:205], v[106:109]
	v_mfma_f32_16x16x32_bf16 v[94:97], v[134:137], v[232:235], v[94:97]
	v_mfma_f32_16x16x32_bf16 v[90:93], v[142:145], v[232:235], v[90:93]
	v_mfma_f32_16x16x32_bf16 v[78:81], v[134:137], v[240:243], v[78:81]
	v_mfma_f32_16x16x32_bf16 v[74:77], v[142:145], v[240:243], v[74:77]
	s_setprio 0
	s_setprio 1
	v_mfma_f32_16x16x32_bf16 v[118:121], v[174:177], v[190:193], v[118:121]
	v_mfma_f32_16x16x32_bf16 v[114:117], v[182:185], v[190:193], v[114:117]
	v_mfma_f32_16x16x32_bf16 v[102:105], v[174:177], v[198:201], v[102:105]
	v_mfma_f32_16x16x32_bf16 v[98:101], v[182:185], v[198:201], v[98:101]
	v_mfma_f32_16x16x32_bf16 v[86:89], v[174:177], v[228:231], v[86:89]
	v_mfma_f32_16x16x32_bf16 v[82:85], v[182:185], v[228:231], v[82:85]
	v_mfma_f32_16x16x32_bf16 v[70:73], v[174:177], v[236:239], v[70:73]
	v_mfma_f32_16x16x32_bf16 v[66:69], v[182:185], v[236:239], v[66:69]
	v_mfma_f32_16x16x32_bf16 v[118:121], v[178:181], v[194:197], v[118:121]
	v_mfma_f32_16x16x32_bf16 v[114:117], v[186:189], v[194:197], v[114:117]
	v_mfma_f32_16x16x32_bf16 v[102:105], v[178:181], v[202:205], v[102:105]
	v_mfma_f32_16x16x32_bf16 v[98:101], v[186:189], v[202:205], v[98:101]
	v_mfma_f32_16x16x32_bf16 v[86:89], v[178:181], v[232:235], v[86:89]
	v_mfma_f32_16x16x32_bf16 v[82:85], v[186:189], v[232:235], v[82:85]
	v_mfma_f32_16x16x32_bf16 v[70:73], v[178:181], v[240:243], v[70:73]
	v_mfma_f32_16x16x32_bf16 v[66:69], v[186:189], v[240:243], v[66:69]
	s_setprio 0
	s_barrier
	s_add_i32 s39, s39, s13
	v_lshl_add_u64 v[166:167], v[244:245], 0, s[14:15]
	s_mov_b32 m0, s39
	ds_read_b128 v[190:193], v157 offset:49152
	ds_read_b128 v[194:197], v157 offset:50176
	ds_read_b128 v[198:201], v157 offset:51200
	ds_read_b128 v[202:205], v157 offset:52224
	ds_read_b128 v[228:231], v157 offset:53248
	ds_read_b128 v[232:235], v157 offset:54272
	ds_read_b128 v[236:239], v157 offset:55296
	ds_read_b128 v[240:243], v157 offset:56320
	global_load_lds_dwordx4 v[166:167], off
	s_add_i32 m0, s39, 0x2000
	s_add_u32 s46, s46, 0x40080
	v_lshl_add_u64 v[166:167], v[246:247], 0, s[14:15]
	s_addc_u32 s47, s47, 0
	s_add_i32 s39, s43, s13
	global_load_lds_dwordx4 v[166:167], off
	v_lshl_add_u64 v[166:167], s[46:47], 0, v[0:1]
	s_mov_b32 m0, s39
	s_nop 0
	global_load_lds_dwordx4 v[166:167], off
	v_lshl_add_u64 v[166:167], s[46:47], 0, v[154:155]
	s_add_i32 m0, s39, 0x2000
	s_nop 0
	global_load_lds_dwordx4 v[166:167], off
	v_lshl_add_u64 v[166:167], v[248:249], 0, s[14:15]
	s_mov_b32 m0, s61
	s_nop 0
	global_load_lds_dwordx4 v[166:167], off
	v_lshl_add_u64 v[166:167], v[250:251], 0, s[14:15]
	s_mov_b32 m0, s62
	s_nop 0
	global_load_lds_dwordx4 v[166:167], off
	s_waitcnt vmcnt(8)
	s_waitcnt lgkmcnt(0)
	s_barrier
	s_setprio 1
	s_waitcnt lgkmcnt(0)
	v_mfma_f32_16x16x32_bf16 v[62:65], v[130:133], v[190:193], v[62:65]
	v_mfma_f32_16x16x32_bf16 v[58:61], v[138:141], v[190:193], v[58:61]
	v_mfma_f32_16x16x32_bf16 v[46:49], v[130:133], v[198:201], v[46:49]
	v_mfma_f32_16x16x32_bf16 v[42:45], v[138:141], v[198:201], v[42:45]
	v_mfma_f32_16x16x32_bf16 v[30:33], v[130:133], v[228:231], v[30:33]
	v_mfma_f32_16x16x32_bf16 v[26:29], v[138:141], v[228:231], v[26:29]
	v_mfma_f32_16x16x32_bf16 v[14:17], v[130:133], v[236:239], v[14:17]
	v_mfma_f32_16x16x32_bf16 v[10:13], v[138:141], v[236:239], v[10:13]
	v_mfma_f32_16x16x32_bf16 v[62:65], v[134:137], v[194:197], v[62:65]
	v_mfma_f32_16x16x32_bf16 v[58:61], v[142:145], v[194:197], v[58:61]
	v_mfma_f32_16x16x32_bf16 v[46:49], v[134:137], v[202:205], v[46:49]
	v_mfma_f32_16x16x32_bf16 v[42:45], v[142:145], v[202:205], v[42:45]
	v_mfma_f32_16x16x32_bf16 v[30:33], v[134:137], v[232:235], v[30:33]
	v_mfma_f32_16x16x32_bf16 v[26:29], v[142:145], v[232:235], v[26:29]
	v_mfma_f32_16x16x32_bf16 v[14:17], v[134:137], v[240:243], v[14:17]
	v_mfma_f32_16x16x32_bf16 v[10:13], v[142:145], v[240:243], v[10:13]
	s_setprio 0
	s_setprio 1
	v_mfma_f32_16x16x32_bf16 v[54:57], v[174:177], v[190:193], v[54:57]
	v_mfma_f32_16x16x32_bf16 v[50:53], v[182:185], v[190:193], v[50:53]
	v_mfma_f32_16x16x32_bf16 v[38:41], v[174:177], v[198:201], v[38:41]
	v_mfma_f32_16x16x32_bf16 v[34:37], v[182:185], v[198:201], v[34:37]
	v_mfma_f32_16x16x32_bf16 v[22:25], v[174:177], v[228:231], v[22:25]
	v_mfma_f32_16x16x32_bf16 v[18:21], v[182:185], v[228:231], v[18:21]
	v_mfma_f32_16x16x32_bf16 v[6:9], v[174:177], v[236:239], v[6:9]
	v_mfma_f32_16x16x32_bf16 v[2:5], v[182:185], v[236:239], v[2:5]
	v_mfma_f32_16x16x32_bf16 v[54:57], v[178:181], v[194:197], v[54:57]
	v_mfma_f32_16x16x32_bf16 v[50:53], v[186:189], v[194:197], v[50:53]
	v_mfma_f32_16x16x32_bf16 v[38:41], v[178:181], v[202:205], v[38:41]
	v_mfma_f32_16x16x32_bf16 v[34:37], v[186:189], v[202:205], v[34:37]
	v_mfma_f32_16x16x32_bf16 v[22:25], v[178:181], v[232:235], v[22:25]
	v_mfma_f32_16x16x32_bf16 v[18:21], v[186:189], v[232:235], v[18:21]
	v_mfma_f32_16x16x32_bf16 v[6:9], v[178:181], v[240:243], v[6:9]
	v_mfma_f32_16x16x32_bf16 v[2:5], v[186:189], v[240:243], v[2:5]
	s_setprio 0
	s_barrier
	s_add_i32 s34, s34, 2
	s_add_u32 s44, s44, 0x100
	s_addc_u32 s45, s45, 0
	s_add_u32 s27, s27, 0x100
	s_addc_u32 s29, s29, 0
	s_cmp_gt_u32 s34, 13
	s_cbranch_scc0 .LBB0_1067
	s_and_b64 vcc, exec, s[8:9]
	s_cbranch_vccz .LBB0_1070
	s_barrier

.LBB0_1251:
	s_andn2_b64 vcc, exec, s[4:5]
	s_cbranch_vccnz .LBB0_1058
	s_branch .LBB0_1058
